# scan: gate math / gelu / aggregate products on channel pairs with v_pk_fma/mul/add_f32 (plain f32, half the VALU instructions)
# speedup vs baseline: 1.0054x; 1.0042x over previous
.Lscan1_staged:
	s_lshr_b32 s0, s23, 4
	s_lshl_b32 s0, s0, 3
	s_add_i32 s0, s0, s21
	s_mul_i32 s55, s0, 0x5f5
	s_lshr_b32 s55, s55, 16
	s_mul_i32 s56, s55, 43
	s_sub_i32 s56, s0, s56
	s_mul_i32 s57, s55, 0x810
	s_mul_i32 s39, s56, 48
	s_add_i32 s57, s57, s39
	s_mul_i32 s44, s57, 0x1800
	s_mul_hi_u32 s45, s57, 0x1800
	s_mul_i32 s39, s37, 0xc0
	s_add_i32 s39, s39, 0xc00
	s_add_u32 s44, s44, s39
	s_addc_u32 s45, s45, 0
	s_add_u32 s44, s44, s28
	s_addc_u32 s45, s45, s29
	s_add_u32 s62, s44, 0xffffb800
	s_addc_u32 s63, s45, -1
	global_load_dword v59, v233, s[62:63]
	s_add_u32 s62, s62, 0x1800
	s_addc_u32 s63, s63, 0
	global_load_dword v61, v233, s[62:63]
	s_add_u32 s62, s62, 0x1800
	s_addc_u32 s63, s63, 0
	global_load_dword v63, v233, s[62:63]
	s_mov_b64 s[62:63], s[44:45]
	global_load_dword v66, v233, s[62:63]
	s_add_u32 s62, s62, 0x1800
	s_addc_u32 s63, s63, 0
	global_load_dword v67, v233, s[62:63]
	s_add_u32 s62, s62, 0x1800
	s_addc_u32 s63, s63, 0
	global_load_dword v68, v233, s[62:63]
	s_add_u32 s62, s62, 0x1800
	s_addc_u32 s63, s63, 0
	global_load_dword v69, v233, s[62:63]
	s_add_u32 s62, s62, 0x1800
	s_addc_u32 s63, s63, 0
	global_load_dword v70, v233, s[62:63]
	s_add_u32 s62, s62, 0x1800
	s_addc_u32 s63, s63, 0
	global_load_dword v71, v233, s[62:63]
	s_add_u32 s62, s62, 0x1800
	s_addc_u32 s63, s63, 0
	global_load_dword v72, v233, s[62:63]
	s_add_u32 s62, s62, 0x1800
	s_addc_u32 s63, s63, 0
	global_load_dword v73, v233, s[62:63]
	s_add_u32 s62, s62, 0x1800
	s_addc_u32 s63, s63, 0
	global_load_dword v74, v233, s[62:63]
	s_add_u32 s62, s62, 0x1800
	s_addc_u32 s63, s63, 0
	global_load_dword v75, v233, s[62:63]
	s_add_u32 s62, s62, 0x1800
	s_addc_u32 s63, s63, 0
	global_load_dword v76, v233, s[62:63]
	s_add_u32 s62, s62, 0x1800
	s_addc_u32 s63, s63, 0
	global_load_dword v77, v233, s[62:63]
	s_add_u32 s62, s62, 0x1800
	s_addc_u32 s63, s63, 0
	global_load_dword v78, v233, s[62:63]
	s_add_u32 s62, s62, 0x1800
	s_addc_u32 s63, s63, 0
	global_load_dword v79, v233, s[62:63]
	s_add_u32 s62, s62, 0x1800
	s_addc_u32 s63, s63, 0
	global_load_dword v80, v233, s[62:63]
	s_add_u32 s62, s62, 0x1800
	s_addc_u32 s63, s63, 0
	global_load_dword v81, v233, s[62:63]
	s_add_u32 s62, s62, 0x1800
	s_addc_u32 s63, s63, 0
	s_mov_b64 s[44:45], s[62:63]
	s_mul_i32 s39, s37, 0x180
	s_add_u32 s62, s8, s39
	s_addc_u32 s63, s9, 0
	global_load_dwordx2 v[48:49], v234, s[62:63]
	s_add_u32 s62, s62, 0x1800
	s_addc_u32 s63, s63, 0
	global_load_dwordx2 v[50:51], v234, s[62:63]
	s_add_u32 s62, s62, 0x1800
	s_addc_u32 s63, s63, 0
	global_load_dwordx2 v[52:53], v234, s[62:63]
	s_add_u32 s62, s62, 0x1800
	s_addc_u32 s63, s63, 0
	global_load_dwordx2 v[54:55], v234, s[62:63]
	s_add_u32 s62, s10, s39
	s_addc_u32 s63, s11, 0
	global_load_dwordx2 v[56:57], v234, s[62:63]
	s_mul_i32 s39, s55, 43
	s_add_i32 s39, s39, s56
	s_mul_i32 s39, s39, 0x1800
	s_mul_i32 s0, s37, 0x180
	s_add_i32 s39, s39, s0
	s_add_u32 s62, s30, s39
	s_addc_u32 s63, s31, 0
	v_mov_b32_e32 v0, 0
	v_mov_b32_e32 v24, 1.0
	v_mov_b32_e32 v1, 0
	v_mov_b32_e32 v25, 1.0
	v_mov_b32_e32 v2, 0
	v_mov_b32_e32 v26, 1.0
	v_mov_b32_e32 v3, 0
	v_mov_b32_e32 v27, 1.0
	v_mov_b32_e32 v4, 0
	v_mov_b32_e32 v28, 1.0
	v_mov_b32_e32 v5, 0
	v_mov_b32_e32 v29, 1.0
	v_mov_b32_e32 v6, 0
	v_mov_b32_e32 v30, 1.0
	v_mov_b32_e32 v7, 0
	v_mov_b32_e32 v31, 1.0
	v_mov_b32_e32 v8, 0
	v_mov_b32_e32 v32, 1.0
	v_mov_b32_e32 v9, 0
	v_mov_b32_e32 v33, 1.0
	v_mov_b32_e32 v10, 0
	v_mov_b32_e32 v34, 1.0
	v_mov_b32_e32 v11, 0
	v_mov_b32_e32 v35, 1.0
	v_mov_b32_e32 v12, 0
	v_mov_b32_e32 v36, 1.0
	v_mov_b32_e32 v13, 0
	v_mov_b32_e32 v37, 1.0
	v_mov_b32_e32 v14, 0
	v_mov_b32_e32 v38, 1.0
	v_mov_b32_e32 v15, 0
	v_mov_b32_e32 v39, 1.0
	v_mov_b32_e32 v16, 0
	v_mov_b32_e32 v40, 1.0
	v_mov_b32_e32 v17, 0
	v_mov_b32_e32 v41, 1.0
	v_mov_b32_e32 v18, 0
	v_mov_b32_e32 v42, 1.0
	v_mov_b32_e32 v19, 0
	v_mov_b32_e32 v43, 1.0
	v_mov_b32_e32 v20, 0
	v_mov_b32_e32 v44, 1.0
	v_mov_b32_e32 v21, 0
	v_mov_b32_e32 v45, 1.0
	v_mov_b32_e32 v22, 0
	v_mov_b32_e32 v46, 1.0
	v_mov_b32_e32 v23, 0
	v_mov_b32_e32 v47, 1.0
	s_mov_b64 s[6:7], s[62:63]
	s_mov_b32 s66, 0xbfb8aa3b
	s_mov_b32 s67, 0xbd2ec3ff
	v_mov_b32_e32 v248, 0xbe1d955b
	v_mov_b32_e32 v249, 0xbee35847
	v_mov_b32_e32 v250, 0xbf75fdf0
	v_mov_b32_e32 v251, 0xbfb17218
	s_waitcnt vmcnt(0)
	s_cmp_eq_u32 s56, 0
	s_cbranch_scc1 .Lscan1_hzero
	v_lshlrev_b32_e32 v58, 16, v59
	v_and_b32_e32 v59, 0xffff0000, v59
	v_lshlrev_b32_e32 v60, 16, v61
	v_and_b32_e32 v61, 0xffff0000, v61
	v_lshlrev_b32_e32 v62, 16, v63
	v_and_b32_e32 v63, 0xffff0000, v63
	s_branch .Lscan1_hdone

.Lscan1_sub:
	s_mov_b64 s[62:63], s[44:45]
	global_load_dword v82, v233, s[62:63]
	s_add_u32 s62, s62, 0x1800
	s_addc_u32 s63, s63, 0
	global_load_dword v83, v233, s[62:63]
	s_add_u32 s62, s62, 0x1800
	s_addc_u32 s63, s63, 0
	global_load_dword v84, v233, s[62:63]
	s_add_u32 s62, s62, 0x1800
	s_addc_u32 s63, s63, 0
	global_load_dword v85, v233, s[62:63]
	s_add_u32 s62, s62, 0x1800
	s_addc_u32 s63, s63, 0
	global_load_dword v86, v233, s[62:63]
	s_add_u32 s62, s62, 0x1800
	s_addc_u32 s63, s63, 0
	global_load_dword v87, v233, s[62:63]
	s_add_u32 s62, s62, 0x1800
	s_addc_u32 s63, s63, 0
	global_load_dword v88, v233, s[62:63]
	s_add_u32 s62, s62, 0x1800
	s_addc_u32 s63, s63, 0
	global_load_dword v89, v233, s[62:63]
	s_add_u32 s62, s62, 0x1800
	s_addc_u32 s63, s63, 0
	global_load_dword v90, v233, s[62:63]
	s_add_u32 s62, s62, 0x1800
	s_addc_u32 s63, s63, 0
	global_load_dword v91, v233, s[62:63]
	s_add_u32 s62, s62, 0x1800
	s_addc_u32 s63, s63, 0
	global_load_dword v92, v233, s[62:63]
	s_add_u32 s62, s62, 0x1800
	s_addc_u32 s63, s63, 0
	global_load_dword v93, v233, s[62:63]
	s_add_u32 s62, s62, 0x1800
	s_addc_u32 s63, s63, 0
	global_load_dword v94, v233, s[62:63]
	s_add_u32 s62, s62, 0x1800
	s_addc_u32 s63, s63, 0
	global_load_dword v95, v233, s[62:63]
	s_add_u32 s62, s62, 0x1800
	s_addc_u32 s63, s63, 0
	global_load_dword v96, v233, s[62:63]
	s_add_u32 s62, s62, 0x1800
	s_addc_u32 s63, s63, 0
	global_load_dword v97, v233, s[62:63]
	s_add_u32 s62, s62, 0x1800
	s_addc_u32 s63, s63, 0
	s_mov_b64 s[44:45], s[62:63]
	ds_read_b128 v[110:113], v229 offset:0
	ds_read_b128 v[122:125], v229 offset:19968
	ds_read_b128 v[114:117], v229 offset:64
	ds_read_b128 v[126:129], v229 offset:20032
	ds_read_b128 v[118:121], v229 offset:128
	ds_read_b128 v[130:133], v229 offset:20096
	ds_read_b128 v[150:153], v230
	ds_read_b128 v[154:157], v230 offset:384
	ds_read_b128 v[158:161], v230 offset:768
	s_mov_b32 s62, -1
	s_mov_b32 s63, 0xffff
	s_mov_b64 exec, s[62:63]
	v_lshlrev_b32_e32 v64, 16, v66
	v_and_b32_e32 v65, 0xffff0000, v66
	v_pk_fma_f32 v[242:243], v[58:59], v[48:49], v[56:57]
	v_lshlrev_b32_e32 v58, 16, v67
	v_and_b32_e32 v59, 0xffff0000, v67
	v_pk_fma_f32 v[244:245], v[60:61], v[48:49], v[56:57]
	v_pk_fma_f32 v[242:243], v[60:61], v[50:51], v[242:243]
	v_pk_fma_f32 v[244:245], v[62:63], v[50:51], v[244:245]
	v_pk_fma_f32 v[242:243], v[62:63], v[52:53], v[242:243]
	v_pk_fma_f32 v[244:245], v[64:65], v[52:53], v[244:245]
	v_pk_fma_f32 v[242:243], v[64:65], v[54:55], v[242:243]
	v_pk_fma_f32 v[244:245], v[58:59], v[54:55], v[244:245]
	ds_write_b64 v226, v[242:243] offset:0
	v_cvt_pk_bf16_f32 v246, v242, v243
	ds_write_b64 v226, v[244:245] offset:400
	v_cvt_pk_bf16_f32 v247, v244, v245
	ds_write_b32 v227, v246 offset:0
	ds_write_b32 v227, v247 offset:208
	v_lshlrev_b32_e32 v60, 16, v68
	v_and_b32_e32 v61, 0xffff0000, v68
	v_pk_fma_f32 v[242:243], v[62:63], v[48:49], v[56:57]
	v_lshlrev_b32_e32 v62, 16, v69
	v_and_b32_e32 v63, 0xffff0000, v69
	v_pk_fma_f32 v[244:245], v[64:65], v[48:49], v[56:57]
	v_pk_fma_f32 v[242:243], v[64:65], v[50:51], v[242:243]
	v_pk_fma_f32 v[244:245], v[58:59], v[50:51], v[244:245]
	v_pk_fma_f32 v[242:243], v[58:59], v[52:53], v[242:243]
	v_pk_fma_f32 v[244:245], v[60:61], v[52:53], v[244:245]
	v_pk_fma_f32 v[242:243], v[60:61], v[54:55], v[242:243]
	v_pk_fma_f32 v[244:245], v[62:63], v[54:55], v[244:245]
	ds_write_b64 v226, v[242:243] offset:800
	v_cvt_pk_bf16_f32 v246, v242, v243
	ds_write_b64 v226, v[244:245] offset:1200
	v_cvt_pk_bf16_f32 v247, v244, v245
	ds_write_b32 v227, v246 offset:416
	ds_write_b32 v227, v247 offset:624
	v_lshlrev_b32_e32 v64, 16, v70
	v_and_b32_e32 v65, 0xffff0000, v70
	v_pk_fma_f32 v[242:243], v[58:59], v[48:49], v[56:57]
	v_lshlrev_b32_e32 v58, 16, v71
	v_and_b32_e32 v59, 0xffff0000, v71
	v_pk_fma_f32 v[244:245], v[60:61], v[48:49], v[56:57]
	v_pk_fma_f32 v[242:243], v[60:61], v[50:51], v[242:243]
	v_pk_fma_f32 v[244:245], v[62:63], v[50:51], v[244:245]
	v_pk_fma_f32 v[242:243], v[62:63], v[52:53], v[242:243]
	v_pk_fma_f32 v[244:245], v[64:65], v[52:53], v[244:245]
	v_pk_fma_f32 v[242:243], v[64:65], v[54:55], v[242:243]
	v_pk_fma_f32 v[244:245], v[58:59], v[54:55], v[244:245]
	ds_write_b64 v226, v[242:243] offset:1600
	v_cvt_pk_bf16_f32 v246, v242, v243
	ds_write_b64 v226, v[244:245] offset:2000
	v_cvt_pk_bf16_f32 v247, v244, v245
	ds_write_b32 v227, v246 offset:832
	ds_write_b32 v227, v247 offset:1040
	v_lshlrev_b32_e32 v60, 16, v72
	v_and_b32_e32 v61, 0xffff0000, v72
	v_pk_fma_f32 v[242:243], v[62:63], v[48:49], v[56:57]
	v_lshlrev_b32_e32 v62, 16, v73
	v_and_b32_e32 v63, 0xffff0000, v73
	v_pk_fma_f32 v[244:245], v[64:65], v[48:49], v[56:57]
	v_pk_fma_f32 v[242:243], v[64:65], v[50:51], v[242:243]
	v_pk_fma_f32 v[244:245], v[58:59], v[50:51], v[244:245]
	v_pk_fma_f32 v[242:243], v[58:59], v[52:53], v[242:243]
	v_pk_fma_f32 v[244:245], v[60:61], v[52:53], v[244:245]
	v_pk_fma_f32 v[242:243], v[60:61], v[54:55], v[242:243]
	v_pk_fma_f32 v[244:245], v[62:63], v[54:55], v[244:245]
	ds_write_b64 v226, v[242:243] offset:2400
	v_cvt_pk_bf16_f32 v246, v242, v243
	ds_write_b64 v226, v[244:245] offset:2800
	v_cvt_pk_bf16_f32 v247, v244, v245
	ds_write_b32 v227, v246 offset:1248
	ds_write_b32 v227, v247 offset:1456
	v_lshlrev_b32_e32 v64, 16, v74
	v_and_b32_e32 v65, 0xffff0000, v74
	v_pk_fma_f32 v[242:243], v[58:59], v[48:49], v[56:57]
	v_lshlrev_b32_e32 v58, 16, v75
	v_and_b32_e32 v59, 0xffff0000, v75
	v_pk_fma_f32 v[244:245], v[60:61], v[48:49], v[56:57]
	v_pk_fma_f32 v[242:243], v[60:61], v[50:51], v[242:243]
	v_pk_fma_f32 v[244:245], v[62:63], v[50:51], v[244:245]
	v_pk_fma_f32 v[242:243], v[62:63], v[52:53], v[242:243]
	v_pk_fma_f32 v[244:245], v[64:65], v[52:53], v[244:245]
	v_pk_fma_f32 v[242:243], v[64:65], v[54:55], v[242:243]
	v_pk_fma_f32 v[244:245], v[58:59], v[54:55], v[244:245]
	ds_write_b64 v226, v[242:243] offset:3200
	v_cvt_pk_bf16_f32 v246, v242, v243
	ds_write_b64 v226, v[244:245] offset:3600
	v_cvt_pk_bf16_f32 v247, v244, v245
	ds_write_b32 v227, v246 offset:1664
	ds_write_b32 v227, v247 offset:1872
	v_lshlrev_b32_e32 v60, 16, v76
	v_and_b32_e32 v61, 0xffff0000, v76
	v_pk_fma_f32 v[242:243], v[62:63], v[48:49], v[56:57]
	v_lshlrev_b32_e32 v62, 16, v77
	v_and_b32_e32 v63, 0xffff0000, v77
	v_pk_fma_f32 v[244:245], v[64:65], v[48:49], v[56:57]
	v_pk_fma_f32 v[242:243], v[64:65], v[50:51], v[242:243]
	v_pk_fma_f32 v[244:245], v[58:59], v[50:51], v[244:245]
	v_pk_fma_f32 v[242:243], v[58:59], v[52:53], v[242:243]
	v_pk_fma_f32 v[244:245], v[60:61], v[52:53], v[244:245]
	v_pk_fma_f32 v[242:243], v[60:61], v[54:55], v[242:243]
	v_pk_fma_f32 v[244:245], v[62:63], v[54:55], v[244:245]
	ds_write_b64 v226, v[242:243] offset:4000
	v_cvt_pk_bf16_f32 v246, v242, v243
	ds_write_b64 v226, v[244:245] offset:4400
	v_cvt_pk_bf16_f32 v247, v244, v245
	ds_write_b32 v227, v246 offset:2080
	ds_write_b32 v227, v247 offset:2288
	v_lshlrev_b32_e32 v64, 16, v78
	v_and_b32_e32 v65, 0xffff0000, v78
	v_pk_fma_f32 v[242:243], v[58:59], v[48:49], v[56:57]
	v_lshlrev_b32_e32 v58, 16, v79
	v_and_b32_e32 v59, 0xffff0000, v79
	v_pk_fma_f32 v[244:245], v[60:61], v[48:49], v[56:57]
	v_pk_fma_f32 v[242:243], v[60:61], v[50:51], v[242:243]
	v_pk_fma_f32 v[244:245], v[62:63], v[50:51], v[244:245]
	v_pk_fma_f32 v[242:243], v[62:63], v[52:53], v[242:243]
	v_pk_fma_f32 v[244:245], v[64:65], v[52:53], v[244:245]
	v_pk_fma_f32 v[242:243], v[64:65], v[54:55], v[242:243]
	v_pk_fma_f32 v[244:245], v[58:59], v[54:55], v[244:245]
	ds_write_b64 v226, v[242:243] offset:4800
	v_cvt_pk_bf16_f32 v246, v242, v243
	ds_write_b64 v226, v[244:245] offset:5200
	v_cvt_pk_bf16_f32 v247, v244, v245
	ds_write_b32 v227, v246 offset:2496
	ds_write_b32 v227, v247 offset:2704
	v_lshlrev_b32_e32 v60, 16, v80
	v_and_b32_e32 v61, 0xffff0000, v80
	v_pk_fma_f32 v[242:243], v[62:63], v[48:49], v[56:57]
	v_lshlrev_b32_e32 v62, 16, v81
	v_and_b32_e32 v63, 0xffff0000, v81
	v_pk_fma_f32 v[244:245], v[64:65], v[48:49], v[56:57]
	v_pk_fma_f32 v[242:243], v[64:65], v[50:51], v[242:243]
	v_pk_fma_f32 v[244:245], v[58:59], v[50:51], v[244:245]
	v_pk_fma_f32 v[242:243], v[58:59], v[52:53], v[242:243]
	v_pk_fma_f32 v[244:245], v[60:61], v[52:53], v[244:245]
	v_pk_fma_f32 v[242:243], v[60:61], v[54:55], v[242:243]
	v_pk_fma_f32 v[244:245], v[62:63], v[54:55], v[244:245]
	ds_write_b64 v226, v[242:243] offset:5600
	v_cvt_pk_bf16_f32 v246, v242, v243
	ds_write_b64 v226, v[244:245] offset:6000
	v_cvt_pk_bf16_f32 v247, v244, v245
	ds_write_b32 v227, v246 offset:2912
	ds_write_b32 v227, v247 offset:3120
	s_mov_b64 exec, -1
	s_waitcnt lgkmcnt(0)
	ds_read_b128 v[98:101], v228 offset:0
	ds_read_b128 v[102:105], v228 offset:64
	ds_read_b128 v[106:109], v228 offset:128
	ds_read_b128 v[162:165], v231
	s_waitcnt lgkmcnt(0)
	v_mfma_f32_16x16x32_bf16 v[134:137], v[110:113], v[98:101], 0
	v_mfma_f32_16x16x32_bf16 v[138:141], v[122:125], v[98:101], 0
	v_mfma_f32_16x16x32_bf16 v[134:137], v[114:117], v[102:105], v[134:137]
	v_mfma_f32_16x16x32_bf16 v[138:141], v[126:129], v[102:105], v[138:141]
	v_mfma_f32_16x16x32_bf16 v[134:137], v[118:121], v[106:109], v[134:137]
	v_mfma_f32_16x16x32_bf16 v[138:141], v[130:133], v[106:109], v[138:141]
	ds_read_b128 v[110:113], v229 offset:3328
	ds_read_b128 v[122:125], v229 offset:23296
	ds_read_b128 v[114:117], v229 offset:3392
	ds_read_b128 v[126:129], v229 offset:23360
	ds_read_b128 v[118:121], v229 offset:3456
	ds_read_b128 v[130:133], v229 offset:23424
	s_nop 7
	s_nop 7
	v_pk_fma_f32 v[166:167], v[134:135], s[66:67], v[150:151] op_sel_hi:[1,0,1]
	v_pk_fma_f32 v[168:169], v[136:137], s[66:67], v[152:153] op_sel_hi:[1,0,1]
	v_pk_fma_f32 v[204:205], v[138:139], s[66:67], v[154:155] op_sel_hi:[1,0,1]
	v_pk_fma_f32 v[206:207], v[140:141], s[66:67], v[156:157] op_sel_hi:[1,0,1]
	v_exp_f32_e32 v166, v166
	v_exp_f32_e32 v167, v167
	v_exp_f32_e32 v168, v168
	v_exp_f32_e32 v169, v169
	v_exp_f32_e32 v204, v204
	v_exp_f32_e32 v205, v205
	v_exp_f32_e32 v206, v206
	v_exp_f32_e32 v207, v207
	v_pk_add_f32 v[166:167], v[166:167], 1.0 op_sel_hi:[1,0]
	v_pk_add_f32 v[168:169], v[168:169], 1.0 op_sel_hi:[1,0]
	v_pk_add_f32 v[204:205], v[204:205], 1.0 op_sel_hi:[1,0]
	v_pk_add_f32 v[206:207], v[206:207], 1.0 op_sel_hi:[1,0]
	v_rcp_f32_e32 v166, v166
	v_rcp_f32_e32 v167, v167
	v_rcp_f32_e32 v168, v168
	v_rcp_f32_e32 v169, v169
	v_rcp_f32_e32 v204, v204
	v_rcp_f32_e32 v205, v205
	v_rcp_f32_e32 v206, v206
	v_rcp_f32_e32 v207, v207
	v_pk_mul_f32 v[208:209], v[158:159], v[166:167]
	v_pk_mul_f32 v[210:211], v[160:161], v[168:169]
	v_pk_mul_f32 v[204:205], v[162:163], v[204:205]
	v_pk_mul_f32 v[206:207], v[164:165], v[206:207]
	ds_read_b128 v[150:153], v230 offset:64
	ds_read_b128 v[154:157], v230 offset:448
	ds_read_b128 v[158:161], v230 offset:832
	ds_read_b128 v[162:165], v231 offset:64
	v_exp_f32_e32 v166, v208
	v_exp_f32_e32 v167, v209
	v_exp_f32_e32 v168, v210
	v_exp_f32_e32 v169, v211
	v_pk_fma_f32 v[216:217], v[208:209], s[66:67], v[248:249] op_sel:[0,1,0] op_sel_hi:[1,1,0]
	v_pk_fma_f32 v[218:219], v[210:211], s[66:67], v[248:249] op_sel:[0,1,0] op_sel_hi:[1,1,0]
	v_pk_fma_f32 v[216:217], v[208:209], v[216:217], v[248:249] op_sel:[0,0,1] op_sel_hi:[1,1,1]
	v_pk_fma_f32 v[218:219], v[210:211], v[218:219], v[248:249] op_sel:[0,0,1] op_sel_hi:[1,1,1]
	v_min3_f32 v212, v208, v209, v210
	v_pk_fma_f32 v[216:217], v[208:209], v[216:217], v[250:251] op_sel_hi:[1,1,0]
	v_pk_fma_f32 v[218:219], v[210:211], v[218:219], v[250:251] op_sel_hi:[1,1,0]
	v_min_f32_e32 v212, v212, v211
	v_pk_fma_f32 v[216:217], v[208:209], v[216:217], v[250:251] op_sel:[0,0,1] op_sel_hi:[1,1,1]
	v_pk_fma_f32 v[218:219], v[210:211], v[218:219], v[250:251] op_sel:[0,0,1] op_sel_hi:[1,1,1]
	v_cmp_nlt_f32_e32 vcc, 0xbe38aa3b, v212
	v_pk_mul_f32 v[216:217], v[216:217], v[208:209]
	v_pk_mul_f32 v[218:219], v[218:219], v[210:211]
	s_cbranch_vccnz .Lscan1_far0
.Lscan1_back0:
	v_sqrt_f32_e32 v216, v216
	v_sqrt_f32_e32 v217, v217
	v_sqrt_f32_e32 v218, v218
	v_sqrt_f32_e32 v219, v219
	v_pk_mul_f32 v[204:205], v[204:205], v[216:217]
	v_pk_mul_f32 v[206:207], v[206:207], v[218:219]
	s_waitcnt lgkmcnt(0)
	v_mfma_f32_16x16x32_bf16 v[142:145], v[110:113], v[98:101], 0
	v_mfma_f32_16x16x32_bf16 v[146:149], v[122:125], v[98:101], 0
	v_mfma_f32_16x16x32_bf16 v[142:145], v[114:117], v[102:105], v[142:145]
	v_mfma_f32_16x16x32_bf16 v[146:149], v[126:129], v[102:105], v[146:149]
	v_mfma_f32_16x16x32_bf16 v[142:145], v[118:121], v[106:109], v[142:145]
	v_mfma_f32_16x16x32_bf16 v[146:149], v[130:133], v[106:109], v[146:149]
	s_nop 1
	v_fmac_f32_dpp v204, v204, v166 row_shr:1 row_mask:0xf bank_mask:0xf bound_ctrl:1
	v_fmac_f32_dpp v205, v205, v167 row_shr:1 row_mask:0xf bank_mask:0xf bound_ctrl:1
	v_fmac_f32_dpp v206, v206, v168 row_shr:1 row_mask:0xf bank_mask:0xf bound_ctrl:1
	v_fmac_f32_dpp v207, v207, v169 row_shr:1 row_mask:0xf bank_mask:0xf bound_ctrl:1
	v_mul_f32_dpp v166, v166, v166 row_shr:1 row_mask:0xf bank_mask:0xf
	v_mul_f32_dpp v167, v167, v167 row_shr:1 row_mask:0xf bank_mask:0xf
	v_mul_f32_dpp v168, v168, v168 row_shr:1 row_mask:0xf bank_mask:0xf
	v_mul_f32_dpp v169, v169, v169 row_shr:1 row_mask:0xf bank_mask:0xf
	v_fmac_f32_dpp v204, v204, v166 row_shr:2 row_mask:0xf bank_mask:0xf bound_ctrl:1
	v_fmac_f32_dpp v205, v205, v167 row_shr:2 row_mask:0xf bank_mask:0xf bound_ctrl:1
	v_fmac_f32_dpp v206, v206, v168 row_shr:2 row_mask:0xf bank_mask:0xf bound_ctrl:1
	v_fmac_f32_dpp v207, v207, v169 row_shr:2 row_mask:0xf bank_mask:0xf bound_ctrl:1
	v_mul_f32_dpp v166, v166, v166 row_shr:2 row_mask:0xf bank_mask:0xf
	v_mul_f32_dpp v167, v167, v167 row_shr:2 row_mask:0xf bank_mask:0xf
	v_mul_f32_dpp v168, v168, v168 row_shr:2 row_mask:0xf bank_mask:0xf
	v_mul_f32_dpp v169, v169, v169 row_shr:2 row_mask:0xf bank_mask:0xf
	v_fmac_f32_dpp v204, v204, v166 row_shr:4 row_mask:0xf bank_mask:0xf bound_ctrl:1
	v_fmac_f32_dpp v205, v205, v167 row_shr:4 row_mask:0xf bank_mask:0xf bound_ctrl:1
	v_fmac_f32_dpp v206, v206, v168 row_shr:4 row_mask:0xf bank_mask:0xf bound_ctrl:1
	v_fmac_f32_dpp v207, v207, v169 row_shr:4 row_mask:0xf bank_mask:0xf bound_ctrl:1
	v_mul_f32_dpp v166, v166, v166 row_shr:4 row_mask:0xf bank_mask:0xf
	v_mul_f32_dpp v167, v167, v167 row_shr:4 row_mask:0xf bank_mask:0xf
	v_mul_f32_dpp v168, v168, v168 row_shr:4 row_mask:0xf bank_mask:0xf
	v_mul_f32_dpp v169, v169, v169 row_shr:4 row_mask:0xf bank_mask:0xf
	v_fmac_f32_dpp v204, v204, v166 row_shr:8 row_mask:0xf bank_mask:0xf bound_ctrl:1
	v_fmac_f32_dpp v205, v205, v167 row_shr:8 row_mask:0xf bank_mask:0xf bound_ctrl:1
	v_fmac_f32_dpp v206, v206, v168 row_shr:8 row_mask:0xf bank_mask:0xf bound_ctrl:1
	v_fmac_f32_dpp v207, v207, v169 row_shr:8 row_mask:0xf bank_mask:0xf bound_ctrl:1
	v_mul_f32_dpp v166, v166, v166 row_shr:8 row_mask:0xf bank_mask:0xf
	v_mul_f32_dpp v167, v167, v167 row_shr:8 row_mask:0xf bank_mask:0xf
	v_mul_f32_dpp v168, v168, v168 row_shr:8 row_mask:0xf bank_mask:0xf
	v_mul_f32_dpp v169, v169, v169 row_shr:8 row_mask:0xf bank_mask:0xf
	v_fma_f32 v208, v166, v0, v204
	v_fma_f32 v209, v167, v1, v205
	v_fma_f32 v210, v168, v2, v206
	v_fma_f32 v211, v169, v3, v207
	ds_bpermute_b32 v0, v232, v208
	ds_bpermute_b32 v1, v232, v209
	ds_bpermute_b32 v2, v232, v210
	ds_bpermute_b32 v3, v232, v211
	ds_bpermute_b32 v222, v232, v166
	ds_bpermute_b32 v223, v232, v167
	ds_bpermute_b32 v224, v232, v168
	ds_bpermute_b32 v225, v232, v169
	ds_read_b128 v[110:113], v229 offset:6656
	ds_read_b128 v[122:125], v229 offset:26624
	ds_read_b128 v[114:117], v229 offset:6720
	ds_read_b128 v[126:129], v229 offset:26688
	ds_read_b128 v[118:121], v229 offset:6784
	ds_read_b128 v[130:133], v229 offset:26752
	v_pk_fma_f32 v[166:167], v[142:143], s[66:67], v[150:151] op_sel_hi:[1,0,1]
	v_pk_fma_f32 v[168:169], v[144:145], s[66:67], v[152:153] op_sel_hi:[1,0,1]
	v_pk_fma_f32 v[204:205], v[146:147], s[66:67], v[154:155] op_sel_hi:[1,0,1]
	v_pk_fma_f32 v[206:207], v[148:149], s[66:67], v[156:157] op_sel_hi:[1,0,1]
	v_exp_f32_e32 v166, v166
	v_exp_f32_e32 v167, v167
	v_exp_f32_e32 v168, v168
	v_exp_f32_e32 v169, v169
	v_exp_f32_e32 v204, v204
	v_exp_f32_e32 v205, v205
	v_exp_f32_e32 v206, v206
	v_exp_f32_e32 v207, v207
	v_pk_add_f32 v[166:167], v[166:167], 1.0 op_sel_hi:[1,0]
	v_pk_add_f32 v[168:169], v[168:169], 1.0 op_sel_hi:[1,0]
	v_pk_add_f32 v[204:205], v[204:205], 1.0 op_sel_hi:[1,0]
	v_pk_add_f32 v[206:207], v[206:207], 1.0 op_sel_hi:[1,0]
	v_rcp_f32_e32 v166, v166
	v_rcp_f32_e32 v167, v167
	v_rcp_f32_e32 v168, v168
	v_rcp_f32_e32 v169, v169
	v_rcp_f32_e32 v204, v204
	v_rcp_f32_e32 v205, v205
	v_rcp_f32_e32 v206, v206
	v_rcp_f32_e32 v207, v207
	v_pk_mul_f32 v[208:209], v[158:159], v[166:167]
	v_pk_mul_f32 v[210:211], v[160:161], v[168:169]
	v_pk_mul_f32 v[204:205], v[162:163], v[204:205]
	v_pk_mul_f32 v[206:207], v[164:165], v[206:207]
	ds_read_b128 v[150:153], v230 offset:128
	ds_read_b128 v[154:157], v230 offset:512
	ds_read_b128 v[158:161], v230 offset:896
	ds_read_b128 v[162:165], v231 offset:128
	v_exp_f32_e32 v166, v208
	v_exp_f32_e32 v167, v209
	v_exp_f32_e32 v168, v210
	v_exp_f32_e32 v169, v211
	v_pk_fma_f32 v[216:217], v[208:209], s[66:67], v[248:249] op_sel:[0,1,0] op_sel_hi:[1,1,0]
	v_pk_fma_f32 v[218:219], v[210:211], s[66:67], v[248:249] op_sel:[0,1,0] op_sel_hi:[1,1,0]
	v_pk_fma_f32 v[216:217], v[208:209], v[216:217], v[248:249] op_sel:[0,0,1] op_sel_hi:[1,1,1]
	v_pk_fma_f32 v[218:219], v[210:211], v[218:219], v[248:249] op_sel:[0,0,1] op_sel_hi:[1,1,1]
	v_min3_f32 v212, v208, v209, v210
	v_pk_fma_f32 v[216:217], v[208:209], v[216:217], v[250:251] op_sel_hi:[1,1,0]
	v_pk_fma_f32 v[218:219], v[210:211], v[218:219], v[250:251] op_sel_hi:[1,1,0]
	v_min_f32_e32 v212, v212, v211
	v_pk_fma_f32 v[216:217], v[208:209], v[216:217], v[250:251] op_sel:[0,0,1] op_sel_hi:[1,1,1]
	v_pk_fma_f32 v[218:219], v[210:211], v[218:219], v[250:251] op_sel:[0,0,1] op_sel_hi:[1,1,1]
	v_cmp_nlt_f32_e32 vcc, 0xbe38aa3b, v212
	v_pk_mul_f32 v[216:217], v[216:217], v[208:209]
	v_pk_mul_f32 v[218:219], v[218:219], v[210:211]
	s_cbranch_vccnz .Lscan1_far1
.Lscan1_back1:
	v_sqrt_f32_e32 v216, v216
	v_sqrt_f32_e32 v217, v217
	v_sqrt_f32_e32 v218, v218
	v_sqrt_f32_e32 v219, v219
	v_pk_mul_f32 v[204:205], v[204:205], v[216:217]
	v_pk_mul_f32 v[206:207], v[206:207], v[218:219]
	s_waitcnt lgkmcnt(0)
	v_pk_mul_f32 v[24:25], v[24:25], v[222:223]
	v_pk_mul_f32 v[26:27], v[26:27], v[224:225]
	v_mfma_f32_16x16x32_bf16 v[134:137], v[110:113], v[98:101], 0
	v_mfma_f32_16x16x32_bf16 v[138:141], v[122:125], v[98:101], 0
	v_mfma_f32_16x16x32_bf16 v[134:137], v[114:117], v[102:105], v[134:137]
	v_mfma_f32_16x16x32_bf16 v[138:141], v[126:129], v[102:105], v[138:141]
	v_mfma_f32_16x16x32_bf16 v[134:137], v[118:121], v[106:109], v[134:137]
	v_mfma_f32_16x16x32_bf16 v[138:141], v[130:133], v[106:109], v[138:141]
	s_nop 1
	v_fmac_f32_dpp v204, v204, v166 row_shr:1 row_mask:0xf bank_mask:0xf bound_ctrl:1
	v_fmac_f32_dpp v205, v205, v167 row_shr:1 row_mask:0xf bank_mask:0xf bound_ctrl:1
	v_fmac_f32_dpp v206, v206, v168 row_shr:1 row_mask:0xf bank_mask:0xf bound_ctrl:1
	v_fmac_f32_dpp v207, v207, v169 row_shr:1 row_mask:0xf bank_mask:0xf bound_ctrl:1
	v_mul_f32_dpp v166, v166, v166 row_shr:1 row_mask:0xf bank_mask:0xf
	v_mul_f32_dpp v167, v167, v167 row_shr:1 row_mask:0xf bank_mask:0xf
	v_mul_f32_dpp v168, v168, v168 row_shr:1 row_mask:0xf bank_mask:0xf
	v_mul_f32_dpp v169, v169, v169 row_shr:1 row_mask:0xf bank_mask:0xf
	v_fmac_f32_dpp v204, v204, v166 row_shr:2 row_mask:0xf bank_mask:0xf bound_ctrl:1
	v_fmac_f32_dpp v205, v205, v167 row_shr:2 row_mask:0xf bank_mask:0xf bound_ctrl:1
	v_fmac_f32_dpp v206, v206, v168 row_shr:2 row_mask:0xf bank_mask:0xf bound_ctrl:1
	v_fmac_f32_dpp v207, v207, v169 row_shr:2 row_mask:0xf bank_mask:0xf bound_ctrl:1
	v_mul_f32_dpp v166, v166, v166 row_shr:2 row_mask:0xf bank_mask:0xf
	v_mul_f32_dpp v167, v167, v167 row_shr:2 row_mask:0xf bank_mask:0xf
	v_mul_f32_dpp v168, v168, v168 row_shr:2 row_mask:0xf bank_mask:0xf
	v_mul_f32_dpp v169, v169, v169 row_shr:2 row_mask:0xf bank_mask:0xf
	v_fmac_f32_dpp v204, v204, v166 row_shr:4 row_mask:0xf bank_mask:0xf bound_ctrl:1
	v_fmac_f32_dpp v205, v205, v167 row_shr:4 row_mask:0xf bank_mask:0xf bound_ctrl:1
	v_fmac_f32_dpp v206, v206, v168 row_shr:4 row_mask:0xf bank_mask:0xf bound_ctrl:1
	v_fmac_f32_dpp v207, v207, v169 row_shr:4 row_mask:0xf bank_mask:0xf bound_ctrl:1
	v_mul_f32_dpp v166, v166, v166 row_shr:4 row_mask:0xf bank_mask:0xf
	v_mul_f32_dpp v167, v167, v167 row_shr:4 row_mask:0xf bank_mask:0xf
	v_mul_f32_dpp v168, v168, v168 row_shr:4 row_mask:0xf bank_mask:0xf
	v_mul_f32_dpp v169, v169, v169 row_shr:4 row_mask:0xf bank_mask:0xf
	v_fmac_f32_dpp v204, v204, v166 row_shr:8 row_mask:0xf bank_mask:0xf bound_ctrl:1
	v_fmac_f32_dpp v205, v205, v167 row_shr:8 row_mask:0xf bank_mask:0xf bound_ctrl:1
	v_fmac_f32_dpp v206, v206, v168 row_shr:8 row_mask:0xf bank_mask:0xf bound_ctrl:1
	v_fmac_f32_dpp v207, v207, v169 row_shr:8 row_mask:0xf bank_mask:0xf bound_ctrl:1
	v_mul_f32_dpp v166, v166, v166 row_shr:8 row_mask:0xf bank_mask:0xf
	v_mul_f32_dpp v167, v167, v167 row_shr:8 row_mask:0xf bank_mask:0xf
	v_mul_f32_dpp v168, v168, v168 row_shr:8 row_mask:0xf bank_mask:0xf
	v_mul_f32_dpp v169, v169, v169 row_shr:8 row_mask:0xf bank_mask:0xf
	v_fma_f32 v208, v166, v4, v204
	v_fma_f32 v209, v167, v5, v205
	v_fma_f32 v210, v168, v6, v206
	v_fma_f32 v211, v169, v7, v207
	ds_bpermute_b32 v4, v232, v208
	ds_bpermute_b32 v5, v232, v209
	ds_bpermute_b32 v6, v232, v210
	ds_bpermute_b32 v7, v232, v211
	ds_bpermute_b32 v222, v232, v166
	ds_bpermute_b32 v223, v232, v167
	ds_bpermute_b32 v224, v232, v168
	ds_bpermute_b32 v225, v232, v169
	ds_read_b128 v[110:113], v229 offset:9984
	ds_read_b128 v[122:125], v229 offset:29952
	ds_read_b128 v[114:117], v229 offset:10048
	ds_read_b128 v[126:129], v229 offset:30016
	ds_read_b128 v[118:121], v229 offset:10112
	ds_read_b128 v[130:133], v229 offset:30080
	v_pk_fma_f32 v[166:167], v[134:135], s[66:67], v[150:151] op_sel_hi:[1,0,1]
	v_pk_fma_f32 v[168:169], v[136:137], s[66:67], v[152:153] op_sel_hi:[1,0,1]
	v_pk_fma_f32 v[204:205], v[138:139], s[66:67], v[154:155] op_sel_hi:[1,0,1]
	v_pk_fma_f32 v[206:207], v[140:141], s[66:67], v[156:157] op_sel_hi:[1,0,1]
	v_exp_f32_e32 v166, v166
	v_exp_f32_e32 v167, v167
	v_exp_f32_e32 v168, v168
	v_exp_f32_e32 v169, v169
	v_exp_f32_e32 v204, v204
	v_exp_f32_e32 v205, v205
	v_exp_f32_e32 v206, v206
	v_exp_f32_e32 v207, v207
	v_pk_add_f32 v[166:167], v[166:167], 1.0 op_sel_hi:[1,0]
	v_pk_add_f32 v[168:169], v[168:169], 1.0 op_sel_hi:[1,0]
	v_pk_add_f32 v[204:205], v[204:205], 1.0 op_sel_hi:[1,0]
	v_pk_add_f32 v[206:207], v[206:207], 1.0 op_sel_hi:[1,0]
	v_rcp_f32_e32 v166, v166
	v_rcp_f32_e32 v167, v167
	v_rcp_f32_e32 v168, v168
	v_rcp_f32_e32 v169, v169
	v_rcp_f32_e32 v204, v204
	v_rcp_f32_e32 v205, v205
	v_rcp_f32_e32 v206, v206
	v_rcp_f32_e32 v207, v207
	v_pk_mul_f32 v[208:209], v[158:159], v[166:167]
	v_pk_mul_f32 v[210:211], v[160:161], v[168:169]
	v_pk_mul_f32 v[204:205], v[162:163], v[204:205]
	v_pk_mul_f32 v[206:207], v[164:165], v[206:207]
	ds_read_b128 v[150:153], v230 offset:192
	ds_read_b128 v[154:157], v230 offset:576
	ds_read_b128 v[158:161], v230 offset:960
	ds_read_b128 v[162:165], v231 offset:192
	v_exp_f32_e32 v166, v208
	v_exp_f32_e32 v167, v209
	v_exp_f32_e32 v168, v210
	v_exp_f32_e32 v169, v211
	v_pk_fma_f32 v[216:217], v[208:209], s[66:67], v[248:249] op_sel:[0,1,0] op_sel_hi:[1,1,0]
	v_pk_fma_f32 v[218:219], v[210:211], s[66:67], v[248:249] op_sel:[0,1,0] op_sel_hi:[1,1,0]
	v_pk_fma_f32 v[216:217], v[208:209], v[216:217], v[248:249] op_sel:[0,0,1] op_sel_hi:[1,1,1]
	v_pk_fma_f32 v[218:219], v[210:211], v[218:219], v[248:249] op_sel:[0,0,1] op_sel_hi:[1,1,1]
	v_min3_f32 v212, v208, v209, v210
	v_pk_fma_f32 v[216:217], v[208:209], v[216:217], v[250:251] op_sel_hi:[1,1,0]
	v_pk_fma_f32 v[218:219], v[210:211], v[218:219], v[250:251] op_sel_hi:[1,1,0]
	v_min_f32_e32 v212, v212, v211
	v_pk_fma_f32 v[216:217], v[208:209], v[216:217], v[250:251] op_sel:[0,0,1] op_sel_hi:[1,1,1]
	v_pk_fma_f32 v[218:219], v[210:211], v[218:219], v[250:251] op_sel:[0,0,1] op_sel_hi:[1,1,1]
	v_cmp_nlt_f32_e32 vcc, 0xbe38aa3b, v212
	v_pk_mul_f32 v[216:217], v[216:217], v[208:209]
	v_pk_mul_f32 v[218:219], v[218:219], v[210:211]
	s_cbranch_vccnz .Lscan1_far2
.Lscan1_back2:
	v_sqrt_f32_e32 v216, v216
	v_sqrt_f32_e32 v217, v217
	v_sqrt_f32_e32 v218, v218
	v_sqrt_f32_e32 v219, v219
	v_pk_mul_f32 v[204:205], v[204:205], v[216:217]
	v_pk_mul_f32 v[206:207], v[206:207], v[218:219]
	s_waitcnt lgkmcnt(0)
	v_pk_mul_f32 v[28:29], v[28:29], v[222:223]
	v_pk_mul_f32 v[30:31], v[30:31], v[224:225]
	v_mfma_f32_16x16x32_bf16 v[142:145], v[110:113], v[98:101], 0
	v_mfma_f32_16x16x32_bf16 v[146:149], v[122:125], v[98:101], 0
	v_mfma_f32_16x16x32_bf16 v[142:145], v[114:117], v[102:105], v[142:145]
	v_mfma_f32_16x16x32_bf16 v[146:149], v[126:129], v[102:105], v[146:149]
	v_mfma_f32_16x16x32_bf16 v[142:145], v[118:121], v[106:109], v[142:145]
	v_mfma_f32_16x16x32_bf16 v[146:149], v[130:133], v[106:109], v[146:149]
	s_nop 1
	v_fmac_f32_dpp v204, v204, v166 row_shr:1 row_mask:0xf bank_mask:0xf bound_ctrl:1
	v_fmac_f32_dpp v205, v205, v167 row_shr:1 row_mask:0xf bank_mask:0xf bound_ctrl:1
	v_fmac_f32_dpp v206, v206, v168 row_shr:1 row_mask:0xf bank_mask:0xf bound_ctrl:1
	v_fmac_f32_dpp v207, v207, v169 row_shr:1 row_mask:0xf bank_mask:0xf bound_ctrl:1
	v_mul_f32_dpp v166, v166, v166 row_shr:1 row_mask:0xf bank_mask:0xf
	v_mul_f32_dpp v167, v167, v167 row_shr:1 row_mask:0xf bank_mask:0xf
	v_mul_f32_dpp v168, v168, v168 row_shr:1 row_mask:0xf bank_mask:0xf
	v_mul_f32_dpp v169, v169, v169 row_shr:1 row_mask:0xf bank_mask:0xf
	v_fmac_f32_dpp v204, v204, v166 row_shr:2 row_mask:0xf bank_mask:0xf bound_ctrl:1
	v_fmac_f32_dpp v205, v205, v167 row_shr:2 row_mask:0xf bank_mask:0xf bound_ctrl:1
	v_fmac_f32_dpp v206, v206, v168 row_shr:2 row_mask:0xf bank_mask:0xf bound_ctrl:1
	v_fmac_f32_dpp v207, v207, v169 row_shr:2 row_mask:0xf bank_mask:0xf bound_ctrl:1
	v_mul_f32_dpp v166, v166, v166 row_shr:2 row_mask:0xf bank_mask:0xf
	v_mul_f32_dpp v167, v167, v167 row_shr:2 row_mask:0xf bank_mask:0xf
	v_mul_f32_dpp v168, v168, v168 row_shr:2 row_mask:0xf bank_mask:0xf
	v_mul_f32_dpp v169, v169, v169 row_shr:2 row_mask:0xf bank_mask:0xf
	v_fmac_f32_dpp v204, v204, v166 row_shr:4 row_mask:0xf bank_mask:0xf bound_ctrl:1
	v_fmac_f32_dpp v205, v205, v167 row_shr:4 row_mask:0xf bank_mask:0xf bound_ctrl:1
	v_fmac_f32_dpp v206, v206, v168 row_shr:4 row_mask:0xf bank_mask:0xf bound_ctrl:1
	v_fmac_f32_dpp v207, v207, v169 row_shr:4 row_mask:0xf bank_mask:0xf bound_ctrl:1
	v_mul_f32_dpp v166, v166, v166 row_shr:4 row_mask:0xf bank_mask:0xf
	v_mul_f32_dpp v167, v167, v167 row_shr:4 row_mask:0xf bank_mask:0xf
	v_mul_f32_dpp v168, v168, v168 row_shr:4 row_mask:0xf bank_mask:0xf
	v_mul_f32_dpp v169, v169, v169 row_shr:4 row_mask:0xf bank_mask:0xf
	v_fmac_f32_dpp v204, v204, v166 row_shr:8 row_mask:0xf bank_mask:0xf bound_ctrl:1
	v_fmac_f32_dpp v205, v205, v167 row_shr:8 row_mask:0xf bank_mask:0xf bound_ctrl:1
	v_fmac_f32_dpp v206, v206, v168 row_shr:8 row_mask:0xf bank_mask:0xf bound_ctrl:1
	v_fmac_f32_dpp v207, v207, v169 row_shr:8 row_mask:0xf bank_mask:0xf bound_ctrl:1
	v_mul_f32_dpp v166, v166, v166 row_shr:8 row_mask:0xf bank_mask:0xf
	v_mul_f32_dpp v167, v167, v167 row_shr:8 row_mask:0xf bank_mask:0xf
	v_mul_f32_dpp v168, v168, v168 row_shr:8 row_mask:0xf bank_mask:0xf
	v_mul_f32_dpp v169, v169, v169 row_shr:8 row_mask:0xf bank_mask:0xf
	v_fma_f32 v208, v166, v8, v204
	v_fma_f32 v209, v167, v9, v205
	v_fma_f32 v210, v168, v10, v206
	v_fma_f32 v211, v169, v11, v207
	ds_bpermute_b32 v8, v232, v208
	ds_bpermute_b32 v9, v232, v209
	ds_bpermute_b32 v10, v232, v210
	ds_bpermute_b32 v11, v232, v211
	ds_bpermute_b32 v222, v232, v166
	ds_bpermute_b32 v223, v232, v167
	ds_bpermute_b32 v224, v232, v168
	ds_bpermute_b32 v225, v232, v169
	ds_read_b128 v[110:113], v229 offset:13312
	ds_read_b128 v[122:125], v229 offset:33280
	ds_read_b128 v[114:117], v229 offset:13376
	ds_read_b128 v[126:129], v229 offset:33344
	ds_read_b128 v[118:121], v229 offset:13440
	ds_read_b128 v[130:133], v229 offset:33408
	v_pk_fma_f32 v[166:167], v[142:143], s[66:67], v[150:151] op_sel_hi:[1,0,1]
	v_pk_fma_f32 v[168:169], v[144:145], s[66:67], v[152:153] op_sel_hi:[1,0,1]
	v_pk_fma_f32 v[204:205], v[146:147], s[66:67], v[154:155] op_sel_hi:[1,0,1]
	v_pk_fma_f32 v[206:207], v[148:149], s[66:67], v[156:157] op_sel_hi:[1,0,1]
	v_exp_f32_e32 v166, v166
	v_exp_f32_e32 v167, v167
	v_exp_f32_e32 v168, v168
	v_exp_f32_e32 v169, v169
	v_exp_f32_e32 v204, v204
	v_exp_f32_e32 v205, v205
	v_exp_f32_e32 v206, v206
	v_exp_f32_e32 v207, v207
	v_pk_add_f32 v[166:167], v[166:167], 1.0 op_sel_hi:[1,0]
	v_pk_add_f32 v[168:169], v[168:169], 1.0 op_sel_hi:[1,0]
	v_pk_add_f32 v[204:205], v[204:205], 1.0 op_sel_hi:[1,0]
	v_pk_add_f32 v[206:207], v[206:207], 1.0 op_sel_hi:[1,0]
	v_rcp_f32_e32 v166, v166
	v_rcp_f32_e32 v167, v167
	v_rcp_f32_e32 v168, v168
	v_rcp_f32_e32 v169, v169
	v_rcp_f32_e32 v204, v204
	v_rcp_f32_e32 v205, v205
	v_rcp_f32_e32 v206, v206
	v_rcp_f32_e32 v207, v207
	v_pk_mul_f32 v[208:209], v[158:159], v[166:167]
	v_pk_mul_f32 v[210:211], v[160:161], v[168:169]
	v_pk_mul_f32 v[204:205], v[162:163], v[204:205]
	v_pk_mul_f32 v[206:207], v[164:165], v[206:207]
	ds_read_b128 v[150:153], v230 offset:256
	ds_read_b128 v[154:157], v230 offset:640
	ds_read_b128 v[158:161], v230 offset:1024
	ds_read_b128 v[162:165], v231 offset:256
	v_exp_f32_e32 v166, v208
	v_exp_f32_e32 v167, v209
	v_exp_f32_e32 v168, v210
	v_exp_f32_e32 v169, v211
	v_pk_fma_f32 v[216:217], v[208:209], s[66:67], v[248:249] op_sel:[0,1,0] op_sel_hi:[1,1,0]
	v_pk_fma_f32 v[218:219], v[210:211], s[66:67], v[248:249] op_sel:[0,1,0] op_sel_hi:[1,1,0]
	v_pk_fma_f32 v[216:217], v[208:209], v[216:217], v[248:249] op_sel:[0,0,1] op_sel_hi:[1,1,1]
	v_pk_fma_f32 v[218:219], v[210:211], v[218:219], v[248:249] op_sel:[0,0,1] op_sel_hi:[1,1,1]
	v_min3_f32 v212, v208, v209, v210
	v_pk_fma_f32 v[216:217], v[208:209], v[216:217], v[250:251] op_sel_hi:[1,1,0]
	v_pk_fma_f32 v[218:219], v[210:211], v[218:219], v[250:251] op_sel_hi:[1,1,0]
	v_min_f32_e32 v212, v212, v211
	v_pk_fma_f32 v[216:217], v[208:209], v[216:217], v[250:251] op_sel:[0,0,1] op_sel_hi:[1,1,1]
	v_pk_fma_f32 v[218:219], v[210:211], v[218:219], v[250:251] op_sel:[0,0,1] op_sel_hi:[1,1,1]
	v_cmp_nlt_f32_e32 vcc, 0xbe38aa3b, v212
	v_pk_mul_f32 v[216:217], v[216:217], v[208:209]
	v_pk_mul_f32 v[218:219], v[218:219], v[210:211]
	s_cbranch_vccnz .Lscan1_far3
.Lscan1_back3:
	v_sqrt_f32_e32 v216, v216
	v_sqrt_f32_e32 v217, v217
	v_sqrt_f32_e32 v218, v218
	v_sqrt_f32_e32 v219, v219
	v_pk_mul_f32 v[204:205], v[204:205], v[216:217]
	v_pk_mul_f32 v[206:207], v[206:207], v[218:219]
	s_waitcnt lgkmcnt(0)
	v_pk_mul_f32 v[32:33], v[32:33], v[222:223]
	v_pk_mul_f32 v[34:35], v[34:35], v[224:225]
	v_mfma_f32_16x16x32_bf16 v[134:137], v[110:113], v[98:101], 0
	v_mfma_f32_16x16x32_bf16 v[138:141], v[122:125], v[98:101], 0
	v_mfma_f32_16x16x32_bf16 v[134:137], v[114:117], v[102:105], v[134:137]
	v_mfma_f32_16x16x32_bf16 v[138:141], v[126:129], v[102:105], v[138:141]
	v_mfma_f32_16x16x32_bf16 v[134:137], v[118:121], v[106:109], v[134:137]
	v_mfma_f32_16x16x32_bf16 v[138:141], v[130:133], v[106:109], v[138:141]
	s_nop 1
	v_fmac_f32_dpp v204, v204, v166 row_shr:1 row_mask:0xf bank_mask:0xf bound_ctrl:1
	v_fmac_f32_dpp v205, v205, v167 row_shr:1 row_mask:0xf bank_mask:0xf bound_ctrl:1
	v_fmac_f32_dpp v206, v206, v168 row_shr:1 row_mask:0xf bank_mask:0xf bound_ctrl:1
	v_fmac_f32_dpp v207, v207, v169 row_shr:1 row_mask:0xf bank_mask:0xf bound_ctrl:1
	v_mul_f32_dpp v166, v166, v166 row_shr:1 row_mask:0xf bank_mask:0xf
	v_mul_f32_dpp v167, v167, v167 row_shr:1 row_mask:0xf bank_mask:0xf
	v_mul_f32_dpp v168, v168, v168 row_shr:1 row_mask:0xf bank_mask:0xf
	v_mul_f32_dpp v169, v169, v169 row_shr:1 row_mask:0xf bank_mask:0xf
	v_fmac_f32_dpp v204, v204, v166 row_shr:2 row_mask:0xf bank_mask:0xf bound_ctrl:1
	v_fmac_f32_dpp v205, v205, v167 row_shr:2 row_mask:0xf bank_mask:0xf bound_ctrl:1
	v_fmac_f32_dpp v206, v206, v168 row_shr:2 row_mask:0xf bank_mask:0xf bound_ctrl:1
	v_fmac_f32_dpp v207, v207, v169 row_shr:2 row_mask:0xf bank_mask:0xf bound_ctrl:1
	v_mul_f32_dpp v166, v166, v166 row_shr:2 row_mask:0xf bank_mask:0xf
	v_mul_f32_dpp v167, v167, v167 row_shr:2 row_mask:0xf bank_mask:0xf
	v_mul_f32_dpp v168, v168, v168 row_shr:2 row_mask:0xf bank_mask:0xf
	v_mul_f32_dpp v169, v169, v169 row_shr:2 row_mask:0xf bank_mask:0xf
	v_fmac_f32_dpp v204, v204, v166 row_shr:4 row_mask:0xf bank_mask:0xf bound_ctrl:1
	v_fmac_f32_dpp v205, v205, v167 row_shr:4 row_mask:0xf bank_mask:0xf bound_ctrl:1
	v_fmac_f32_dpp v206, v206, v168 row_shr:4 row_mask:0xf bank_mask:0xf bound_ctrl:1
	v_fmac_f32_dpp v207, v207, v169 row_shr:4 row_mask:0xf bank_mask:0xf bound_ctrl:1
	v_mul_f32_dpp v166, v166, v166 row_shr:4 row_mask:0xf bank_mask:0xf
	v_mul_f32_dpp v167, v167, v167 row_shr:4 row_mask:0xf bank_mask:0xf
	v_mul_f32_dpp v168, v168, v168 row_shr:4 row_mask:0xf bank_mask:0xf
	v_mul_f32_dpp v169, v169, v169 row_shr:4 row_mask:0xf bank_mask:0xf
	v_fmac_f32_dpp v204, v204, v166 row_shr:8 row_mask:0xf bank_mask:0xf bound_ctrl:1
	v_fmac_f32_dpp v205, v205, v167 row_shr:8 row_mask:0xf bank_mask:0xf bound_ctrl:1
	v_fmac_f32_dpp v206, v206, v168 row_shr:8 row_mask:0xf bank_mask:0xf bound_ctrl:1
	v_fmac_f32_dpp v207, v207, v169 row_shr:8 row_mask:0xf bank_mask:0xf bound_ctrl:1
	v_mul_f32_dpp v166, v166, v166 row_shr:8 row_mask:0xf bank_mask:0xf
	v_mul_f32_dpp v167, v167, v167 row_shr:8 row_mask:0xf bank_mask:0xf
	v_mul_f32_dpp v168, v168, v168 row_shr:8 row_mask:0xf bank_mask:0xf
	v_mul_f32_dpp v169, v169, v169 row_shr:8 row_mask:0xf bank_mask:0xf
	v_fma_f32 v208, v166, v12, v204
	v_fma_f32 v209, v167, v13, v205
	v_fma_f32 v210, v168, v14, v206
	v_fma_f32 v211, v169, v15, v207
	ds_bpermute_b32 v12, v232, v208
	ds_bpermute_b32 v13, v232, v209
	ds_bpermute_b32 v14, v232, v210
	ds_bpermute_b32 v15, v232, v211
	ds_bpermute_b32 v222, v232, v166
	ds_bpermute_b32 v223, v232, v167
	ds_bpermute_b32 v224, v232, v168
	ds_bpermute_b32 v225, v232, v169
	ds_read_b128 v[110:113], v229 offset:16640
	ds_read_b128 v[122:125], v229 offset:36608
	ds_read_b128 v[114:117], v229 offset:16704
	ds_read_b128 v[126:129], v229 offset:36672
	ds_read_b128 v[118:121], v229 offset:16768
	ds_read_b128 v[130:133], v229 offset:36736
	v_pk_fma_f32 v[166:167], v[134:135], s[66:67], v[150:151] op_sel_hi:[1,0,1]
	v_pk_fma_f32 v[168:169], v[136:137], s[66:67], v[152:153] op_sel_hi:[1,0,1]
	v_pk_fma_f32 v[204:205], v[138:139], s[66:67], v[154:155] op_sel_hi:[1,0,1]
	v_pk_fma_f32 v[206:207], v[140:141], s[66:67], v[156:157] op_sel_hi:[1,0,1]
	v_exp_f32_e32 v166, v166
	v_exp_f32_e32 v167, v167
	v_exp_f32_e32 v168, v168
	v_exp_f32_e32 v169, v169
	v_exp_f32_e32 v204, v204
	v_exp_f32_e32 v205, v205
	v_exp_f32_e32 v206, v206
	v_exp_f32_e32 v207, v207
	v_pk_add_f32 v[166:167], v[166:167], 1.0 op_sel_hi:[1,0]
	v_pk_add_f32 v[168:169], v[168:169], 1.0 op_sel_hi:[1,0]
	v_pk_add_f32 v[204:205], v[204:205], 1.0 op_sel_hi:[1,0]
	v_pk_add_f32 v[206:207], v[206:207], 1.0 op_sel_hi:[1,0]
	v_rcp_f32_e32 v166, v166
	v_rcp_f32_e32 v167, v167
	v_rcp_f32_e32 v168, v168
	v_rcp_f32_e32 v169, v169
	v_rcp_f32_e32 v204, v204
	v_rcp_f32_e32 v205, v205
	v_rcp_f32_e32 v206, v206
	v_rcp_f32_e32 v207, v207
	v_pk_mul_f32 v[208:209], v[158:159], v[166:167]
	v_pk_mul_f32 v[210:211], v[160:161], v[168:169]
	v_pk_mul_f32 v[204:205], v[162:163], v[204:205]
	v_pk_mul_f32 v[206:207], v[164:165], v[206:207]
	ds_read_b128 v[150:153], v230 offset:320
	ds_read_b128 v[154:157], v230 offset:704
	ds_read_b128 v[158:161], v230 offset:1088
	ds_read_b128 v[162:165], v231 offset:320
	v_exp_f32_e32 v166, v208
	v_exp_f32_e32 v167, v209
	v_exp_f32_e32 v168, v210
	v_exp_f32_e32 v169, v211
	v_pk_fma_f32 v[216:217], v[208:209], s[66:67], v[248:249] op_sel:[0,1,0] op_sel_hi:[1,1,0]
	v_pk_fma_f32 v[218:219], v[210:211], s[66:67], v[248:249] op_sel:[0,1,0] op_sel_hi:[1,1,0]
	v_pk_fma_f32 v[216:217], v[208:209], v[216:217], v[248:249] op_sel:[0,0,1] op_sel_hi:[1,1,1]
	v_pk_fma_f32 v[218:219], v[210:211], v[218:219], v[248:249] op_sel:[0,0,1] op_sel_hi:[1,1,1]
	v_min3_f32 v212, v208, v209, v210
	v_pk_fma_f32 v[216:217], v[208:209], v[216:217], v[250:251] op_sel_hi:[1,1,0]
	v_pk_fma_f32 v[218:219], v[210:211], v[218:219], v[250:251] op_sel_hi:[1,1,0]
	v_min_f32_e32 v212, v212, v211
	v_pk_fma_f32 v[216:217], v[208:209], v[216:217], v[250:251] op_sel:[0,0,1] op_sel_hi:[1,1,1]
	v_pk_fma_f32 v[218:219], v[210:211], v[218:219], v[250:251] op_sel:[0,0,1] op_sel_hi:[1,1,1]
	v_cmp_nlt_f32_e32 vcc, 0xbe38aa3b, v212
	v_pk_mul_f32 v[216:217], v[216:217], v[208:209]
	v_pk_mul_f32 v[218:219], v[218:219], v[210:211]
	s_cbranch_vccnz .Lscan1_far4
.Lscan1_back4:
	v_sqrt_f32_e32 v216, v216
	v_sqrt_f32_e32 v217, v217
	v_sqrt_f32_e32 v218, v218
	v_sqrt_f32_e32 v219, v219
	v_pk_mul_f32 v[204:205], v[204:205], v[216:217]
	v_pk_mul_f32 v[206:207], v[206:207], v[218:219]
	s_waitcnt lgkmcnt(0)
	v_pk_mul_f32 v[36:37], v[36:37], v[222:223]
	v_pk_mul_f32 v[38:39], v[38:39], v[224:225]
	v_mfma_f32_16x16x32_bf16 v[142:145], v[110:113], v[98:101], 0
	v_mfma_f32_16x16x32_bf16 v[146:149], v[122:125], v[98:101], 0
	v_mfma_f32_16x16x32_bf16 v[142:145], v[114:117], v[102:105], v[142:145]
	v_mfma_f32_16x16x32_bf16 v[146:149], v[126:129], v[102:105], v[146:149]
	v_mfma_f32_16x16x32_bf16 v[142:145], v[118:121], v[106:109], v[142:145]
	v_mfma_f32_16x16x32_bf16 v[146:149], v[130:133], v[106:109], v[146:149]
	s_nop 1
	v_fmac_f32_dpp v204, v204, v166 row_shr:1 row_mask:0xf bank_mask:0xf bound_ctrl:1
	v_fmac_f32_dpp v205, v205, v167 row_shr:1 row_mask:0xf bank_mask:0xf bound_ctrl:1
	v_fmac_f32_dpp v206, v206, v168 row_shr:1 row_mask:0xf bank_mask:0xf bound_ctrl:1
	v_fmac_f32_dpp v207, v207, v169 row_shr:1 row_mask:0xf bank_mask:0xf bound_ctrl:1
	v_mul_f32_dpp v166, v166, v166 row_shr:1 row_mask:0xf bank_mask:0xf
	v_mul_f32_dpp v167, v167, v167 row_shr:1 row_mask:0xf bank_mask:0xf
	v_mul_f32_dpp v168, v168, v168 row_shr:1 row_mask:0xf bank_mask:0xf
	v_mul_f32_dpp v169, v169, v169 row_shr:1 row_mask:0xf bank_mask:0xf
	v_fmac_f32_dpp v204, v204, v166 row_shr:2 row_mask:0xf bank_mask:0xf bound_ctrl:1
	v_fmac_f32_dpp v205, v205, v167 row_shr:2 row_mask:0xf bank_mask:0xf bound_ctrl:1
	v_fmac_f32_dpp v206, v206, v168 row_shr:2 row_mask:0xf bank_mask:0xf bound_ctrl:1
	v_fmac_f32_dpp v207, v207, v169 row_shr:2 row_mask:0xf bank_mask:0xf bound_ctrl:1
	v_mul_f32_dpp v166, v166, v166 row_shr:2 row_mask:0xf bank_mask:0xf
	v_mul_f32_dpp v167, v167, v167 row_shr:2 row_mask:0xf bank_mask:0xf
	v_mul_f32_dpp v168, v168, v168 row_shr:2 row_mask:0xf bank_mask:0xf
	v_mul_f32_dpp v169, v169, v169 row_shr:2 row_mask:0xf bank_mask:0xf
	v_fmac_f32_dpp v204, v204, v166 row_shr:4 row_mask:0xf bank_mask:0xf bound_ctrl:1
	v_fmac_f32_dpp v205, v205, v167 row_shr:4 row_mask:0xf bank_mask:0xf bound_ctrl:1
	v_fmac_f32_dpp v206, v206, v168 row_shr:4 row_mask:0xf bank_mask:0xf bound_ctrl:1
	v_fmac_f32_dpp v207, v207, v169 row_shr:4 row_mask:0xf bank_mask:0xf bound_ctrl:1
	v_mul_f32_dpp v166, v166, v166 row_shr:4 row_mask:0xf bank_mask:0xf
	v_mul_f32_dpp v167, v167, v167 row_shr:4 row_mask:0xf bank_mask:0xf
	v_mul_f32_dpp v168, v168, v168 row_shr:4 row_mask:0xf bank_mask:0xf
	v_mul_f32_dpp v169, v169, v169 row_shr:4 row_mask:0xf bank_mask:0xf
	v_fmac_f32_dpp v204, v204, v166 row_shr:8 row_mask:0xf bank_mask:0xf bound_ctrl:1
	v_fmac_f32_dpp v205, v205, v167 row_shr:8 row_mask:0xf bank_mask:0xf bound_ctrl:1
	v_fmac_f32_dpp v206, v206, v168 row_shr:8 row_mask:0xf bank_mask:0xf bound_ctrl:1
	v_fmac_f32_dpp v207, v207, v169 row_shr:8 row_mask:0xf bank_mask:0xf bound_ctrl:1
	v_mul_f32_dpp v166, v166, v166 row_shr:8 row_mask:0xf bank_mask:0xf
	v_mul_f32_dpp v167, v167, v167 row_shr:8 row_mask:0xf bank_mask:0xf
	v_mul_f32_dpp v168, v168, v168 row_shr:8 row_mask:0xf bank_mask:0xf
	v_mul_f32_dpp v169, v169, v169 row_shr:8 row_mask:0xf bank_mask:0xf
	v_fma_f32 v208, v166, v16, v204
	v_fma_f32 v209, v167, v17, v205
	v_fma_f32 v210, v168, v18, v206
	v_fma_f32 v211, v169, v19, v207
	ds_bpermute_b32 v16, v232, v208
	ds_bpermute_b32 v17, v232, v209
	ds_bpermute_b32 v18, v232, v210
	ds_bpermute_b32 v19, v232, v211
	ds_bpermute_b32 v222, v232, v166
	ds_bpermute_b32 v223, v232, v167
	ds_bpermute_b32 v224, v232, v168
	ds_bpermute_b32 v225, v232, v169
	v_pk_fma_f32 v[166:167], v[142:143], s[66:67], v[150:151] op_sel_hi:[1,0,1]
	v_pk_fma_f32 v[168:169], v[144:145], s[66:67], v[152:153] op_sel_hi:[1,0,1]
	v_pk_fma_f32 v[204:205], v[146:147], s[66:67], v[154:155] op_sel_hi:[1,0,1]
	v_pk_fma_f32 v[206:207], v[148:149], s[66:67], v[156:157] op_sel_hi:[1,0,1]
	v_exp_f32_e32 v166, v166
	v_exp_f32_e32 v167, v167
	v_exp_f32_e32 v168, v168
	v_exp_f32_e32 v169, v169
	v_exp_f32_e32 v204, v204
	v_exp_f32_e32 v205, v205
	v_exp_f32_e32 v206, v206
	v_exp_f32_e32 v207, v207
	v_pk_add_f32 v[166:167], v[166:167], 1.0 op_sel_hi:[1,0]
	v_pk_add_f32 v[168:169], v[168:169], 1.0 op_sel_hi:[1,0]
	v_pk_add_f32 v[204:205], v[204:205], 1.0 op_sel_hi:[1,0]
	v_pk_add_f32 v[206:207], v[206:207], 1.0 op_sel_hi:[1,0]
	v_rcp_f32_e32 v166, v166
	v_rcp_f32_e32 v167, v167
	v_rcp_f32_e32 v168, v168
	v_rcp_f32_e32 v169, v169
	v_rcp_f32_e32 v204, v204
	v_rcp_f32_e32 v205, v205
	v_rcp_f32_e32 v206, v206
	v_rcp_f32_e32 v207, v207
	v_pk_mul_f32 v[208:209], v[158:159], v[166:167]
	v_pk_mul_f32 v[210:211], v[160:161], v[168:169]
	v_pk_mul_f32 v[204:205], v[162:163], v[204:205]
	v_pk_mul_f32 v[206:207], v[164:165], v[206:207]
	v_exp_f32_e32 v166, v208
	v_exp_f32_e32 v167, v209
	v_exp_f32_e32 v168, v210
	v_exp_f32_e32 v169, v211
	v_pk_fma_f32 v[216:217], v[208:209], s[66:67], v[248:249] op_sel:[0,1,0] op_sel_hi:[1,1,0]
	v_pk_fma_f32 v[218:219], v[210:211], s[66:67], v[248:249] op_sel:[0,1,0] op_sel_hi:[1,1,0]
	v_pk_fma_f32 v[216:217], v[208:209], v[216:217], v[248:249] op_sel:[0,0,1] op_sel_hi:[1,1,1]
	v_pk_fma_f32 v[218:219], v[210:211], v[218:219], v[248:249] op_sel:[0,0,1] op_sel_hi:[1,1,1]
	v_min3_f32 v212, v208, v209, v210
	v_pk_fma_f32 v[216:217], v[208:209], v[216:217], v[250:251] op_sel_hi:[1,1,0]
	v_pk_fma_f32 v[218:219], v[210:211], v[218:219], v[250:251] op_sel_hi:[1,1,0]
	v_min_f32_e32 v212, v212, v211
	v_pk_fma_f32 v[216:217], v[208:209], v[216:217], v[250:251] op_sel:[0,0,1] op_sel_hi:[1,1,1]
	v_pk_fma_f32 v[218:219], v[210:211], v[218:219], v[250:251] op_sel:[0,0,1] op_sel_hi:[1,1,1]
	v_cmp_nlt_f32_e32 vcc, 0xbe38aa3b, v212
	v_pk_mul_f32 v[216:217], v[216:217], v[208:209]
	v_pk_mul_f32 v[218:219], v[218:219], v[210:211]
	s_cbranch_vccnz .Lscan1_far5
.Lscan1_back5:
	v_sqrt_f32_e32 v216, v216
	v_sqrt_f32_e32 v217, v217
	v_sqrt_f32_e32 v218, v218
	v_sqrt_f32_e32 v219, v219
	v_pk_mul_f32 v[204:205], v[204:205], v[216:217]
	v_pk_mul_f32 v[206:207], v[206:207], v[218:219]
	s_waitcnt lgkmcnt(0)
	v_pk_mul_f32 v[40:41], v[40:41], v[222:223]
	v_pk_mul_f32 v[42:43], v[42:43], v[224:225]
	s_nop 1
	v_fmac_f32_dpp v204, v204, v166 row_shr:1 row_mask:0xf bank_mask:0xf bound_ctrl:1
	v_fmac_f32_dpp v205, v205, v167 row_shr:1 row_mask:0xf bank_mask:0xf bound_ctrl:1
	v_fmac_f32_dpp v206, v206, v168 row_shr:1 row_mask:0xf bank_mask:0xf bound_ctrl:1
	v_fmac_f32_dpp v207, v207, v169 row_shr:1 row_mask:0xf bank_mask:0xf bound_ctrl:1
	v_mul_f32_dpp v166, v166, v166 row_shr:1 row_mask:0xf bank_mask:0xf
	v_mul_f32_dpp v167, v167, v167 row_shr:1 row_mask:0xf bank_mask:0xf
	v_mul_f32_dpp v168, v168, v168 row_shr:1 row_mask:0xf bank_mask:0xf
	v_mul_f32_dpp v169, v169, v169 row_shr:1 row_mask:0xf bank_mask:0xf
	v_fmac_f32_dpp v204, v204, v166 row_shr:2 row_mask:0xf bank_mask:0xf bound_ctrl:1
	v_fmac_f32_dpp v205, v205, v167 row_shr:2 row_mask:0xf bank_mask:0xf bound_ctrl:1
	v_fmac_f32_dpp v206, v206, v168 row_shr:2 row_mask:0xf bank_mask:0xf bound_ctrl:1
	v_fmac_f32_dpp v207, v207, v169 row_shr:2 row_mask:0xf bank_mask:0xf bound_ctrl:1
	v_mul_f32_dpp v166, v166, v166 row_shr:2 row_mask:0xf bank_mask:0xf
	v_mul_f32_dpp v167, v167, v167 row_shr:2 row_mask:0xf bank_mask:0xf
	v_mul_f32_dpp v168, v168, v168 row_shr:2 row_mask:0xf bank_mask:0xf
	v_mul_f32_dpp v169, v169, v169 row_shr:2 row_mask:0xf bank_mask:0xf
	v_fmac_f32_dpp v204, v204, v166 row_shr:4 row_mask:0xf bank_mask:0xf bound_ctrl:1
	v_fmac_f32_dpp v205, v205, v167 row_shr:4 row_mask:0xf bank_mask:0xf bound_ctrl:1
	v_fmac_f32_dpp v206, v206, v168 row_shr:4 row_mask:0xf bank_mask:0xf bound_ctrl:1
	v_fmac_f32_dpp v207, v207, v169 row_shr:4 row_mask:0xf bank_mask:0xf bound_ctrl:1
	v_mul_f32_dpp v166, v166, v166 row_shr:4 row_mask:0xf bank_mask:0xf
	v_mul_f32_dpp v167, v167, v167 row_shr:4 row_mask:0xf bank_mask:0xf
	v_mul_f32_dpp v168, v168, v168 row_shr:4 row_mask:0xf bank_mask:0xf
	v_mul_f32_dpp v169, v169, v169 row_shr:4 row_mask:0xf bank_mask:0xf
	v_fmac_f32_dpp v204, v204, v166 row_shr:8 row_mask:0xf bank_mask:0xf bound_ctrl:1
	v_fmac_f32_dpp v205, v205, v167 row_shr:8 row_mask:0xf bank_mask:0xf bound_ctrl:1
	v_fmac_f32_dpp v206, v206, v168 row_shr:8 row_mask:0xf bank_mask:0xf bound_ctrl:1
	v_fmac_f32_dpp v207, v207, v169 row_shr:8 row_mask:0xf bank_mask:0xf bound_ctrl:1
	v_mul_f32_dpp v166, v166, v166 row_shr:8 row_mask:0xf bank_mask:0xf
	v_mul_f32_dpp v167, v167, v167 row_shr:8 row_mask:0xf bank_mask:0xf
	v_mul_f32_dpp v168, v168, v168 row_shr:8 row_mask:0xf bank_mask:0xf
	v_mul_f32_dpp v169, v169, v169 row_shr:8 row_mask:0xf bank_mask:0xf
	v_fma_f32 v208, v166, v20, v204
	v_fma_f32 v209, v167, v21, v205
	v_fma_f32 v210, v168, v22, v206
	v_fma_f32 v211, v169, v23, v207
	ds_bpermute_b32 v20, v232, v208
	ds_bpermute_b32 v21, v232, v209
	ds_bpermute_b32 v22, v232, v210
	ds_bpermute_b32 v23, v232, v211
	ds_bpermute_b32 v222, v232, v166
	ds_bpermute_b32 v223, v232, v167
	ds_bpermute_b32 v224, v232, v168
	ds_bpermute_b32 v225, v232, v169
	s_waitcnt lgkmcnt(0)
	v_pk_mul_f32 v[44:45], v[44:45], v[222:223]
	v_pk_mul_f32 v[46:47], v[46:47], v[224:225]
	s_waitcnt vmcnt(0)
	v_mov_b32_e32 v66, v82
	v_mov_b32_e32 v67, v83
	v_mov_b32_e32 v68, v84
	v_mov_b32_e32 v69, v85
	v_mov_b32_e32 v70, v86
	v_mov_b32_e32 v71, v87
	v_mov_b32_e32 v72, v88
	v_mov_b32_e32 v73, v89
	v_mov_b32_e32 v74, v90
	v_mov_b32_e32 v75, v91
	v_mov_b32_e32 v76, v92
	v_mov_b32_e32 v77, v93
	v_mov_b32_e32 v78, v94
	v_mov_b32_e32 v79, v95
	v_mov_b32_e32 v80, v96
	v_mov_b32_e32 v81, v97
	s_add_i32 s64, s64, 1
	s_cmp_lt_u32 s64, 3
	s_cbranch_scc1 .Lscan1_sub
	s_mov_b32 s62, 0x10001
	s_mov_b32 s63, 0x10001
	s_mov_b64 exec, s[62:63]
	s_add_u32 s62, s6, 0x204000
	s_addc_u32 s63, s7, 0
	global_store_dwordx4 v237, v[24:27], s[6:7] offset:0
	global_store_dwordx4 v237, v[0:3], s[62:63] offset:0
	global_store_dwordx4 v237, v[28:31], s[6:7] offset:64
	global_store_dwordx4 v237, v[4:7], s[62:63] offset:64
	global_store_dwordx4 v237, v[32:35], s[6:7] offset:128
	global_store_dwordx4 v237, v[8:11], s[62:63] offset:128
	global_store_dwordx4 v237, v[36:39], s[6:7] offset:192
	global_store_dwordx4 v237, v[12:15], s[62:63] offset:192
	global_store_dwordx4 v237, v[40:43], s[6:7] offset:256
	global_store_dwordx4 v237, v[16:19], s[62:63] offset:256
	global_store_dwordx4 v237, v[44:47], s[6:7] offset:320
	global_store_dwordx4 v237, v[20:23], s[62:63] offset:320
	s_mov_b64 exec, -1
	s_add_i32 s23, s23, s42

.Lscan1_far0:
	v_cmp_nlt_f32_e32 vcc, 0xbe38aa3b, v208
	v_cmp_nlt_f32_e64 s[62:63], s55, v209
	v_cmp_nlt_f32_e64 s[56:57], s55, v210
	v_fma_f32 v170, -v166, v166, 1.0
	v_fma_f32 v171, -v167, v167, 1.0
	v_fma_f32 v220, -v168, v168, 1.0
	v_fma_f32 v221, -v169, v169, 1.0
	v_cndmask_b32_e32 v216, v216, v170, vcc
	v_cmp_nlt_f32_e32 vcc, 0xbe38aa3b, v211
	v_cndmask_b32_e64 v217, v217, v171, s[62:63]
	v_cndmask_b32_e64 v218, v218, v220, s[56:57]
	s_nop 0
	v_cndmask_b32_e32 v219, v219, v221, vcc
	s_branch .Lscan1_back0

.Lscan2_staged:
	s_lshr_b32 s0, s23, 4
	s_lshl_b32 s0, s0, 3
	s_add_i32 s0, s0, s21
	s_mul_i32 s55, s0, 0x5f5
	s_lshr_b32 s55, s55, 16
	s_mul_i32 s56, s55, 43
	s_sub_i32 s56, s0, s56
	s_mul_i32 s57, s55, 0x810
	s_mul_i32 s39, s56, 48
	s_add_i32 s57, s57, s39
	s_mul_i32 s44, s57, 0x1800
	s_mul_hi_u32 s45, s57, 0x1800
	s_mul_i32 s39, s37, 0xc0
	s_add_i32 s39, s39, 0xc00
	s_add_u32 s44, s44, s39
	s_addc_u32 s45, s45, 0
	s_add_u32 s44, s44, s28
	s_addc_u32 s45, s45, s29
	s_add_u32 s62, s44, 0xffffb800
	s_addc_u32 s63, s45, -1
	global_load_dword v59, v233, s[62:63]
	s_add_u32 s62, s62, 0x1800
	s_addc_u32 s63, s63, 0
	global_load_dword v61, v233, s[62:63]
	s_add_u32 s62, s62, 0x1800
	s_addc_u32 s63, s63, 0
	global_load_dword v63, v233, s[62:63]
	s_mov_b64 s[62:63], s[44:45]
	global_load_dword v66, v233, s[62:63]
	s_add_u32 s62, s62, 0x1800
	s_addc_u32 s63, s63, 0
	global_load_dword v67, v233, s[62:63]
	s_add_u32 s62, s62, 0x1800
	s_addc_u32 s63, s63, 0
	global_load_dword v68, v233, s[62:63]
	s_add_u32 s62, s62, 0x1800
	s_addc_u32 s63, s63, 0
	global_load_dword v69, v233, s[62:63]
	s_add_u32 s62, s62, 0x1800
	s_addc_u32 s63, s63, 0
	global_load_dword v70, v233, s[62:63]
	s_add_u32 s62, s62, 0x1800
	s_addc_u32 s63, s63, 0
	global_load_dword v71, v233, s[62:63]
	s_add_u32 s62, s62, 0x1800
	s_addc_u32 s63, s63, 0
	global_load_dword v72, v233, s[62:63]
	s_add_u32 s62, s62, 0x1800
	s_addc_u32 s63, s63, 0
	global_load_dword v73, v233, s[62:63]
	s_add_u32 s62, s62, 0x1800
	s_addc_u32 s63, s63, 0
	global_load_dword v74, v233, s[62:63]
	s_add_u32 s62, s62, 0x1800
	s_addc_u32 s63, s63, 0
	global_load_dword v75, v233, s[62:63]
	s_add_u32 s62, s62, 0x1800
	s_addc_u32 s63, s63, 0
	global_load_dword v76, v233, s[62:63]
	s_add_u32 s62, s62, 0x1800
	s_addc_u32 s63, s63, 0
	global_load_dword v77, v233, s[62:63]
	s_add_u32 s62, s62, 0x1800
	s_addc_u32 s63, s63, 0
	global_load_dword v78, v233, s[62:63]
	s_add_u32 s62, s62, 0x1800
	s_addc_u32 s63, s63, 0
	global_load_dword v79, v233, s[62:63]
	s_add_u32 s62, s62, 0x1800
	s_addc_u32 s63, s63, 0
	global_load_dword v80, v233, s[62:63]
	s_add_u32 s62, s62, 0x1800
	s_addc_u32 s63, s63, 0
	global_load_dword v81, v233, s[62:63]
	s_add_u32 s62, s62, 0x1800
	s_addc_u32 s63, s63, 0
	s_mov_b64 s[44:45], s[62:63]
	s_mul_i32 s39, s37, 0x180
	s_add_u32 s62, s8, s39
	s_addc_u32 s63, s9, 0
	global_load_dwordx2 v[48:49], v234, s[62:63]
	s_add_u32 s62, s62, 0x1800
	s_addc_u32 s63, s63, 0
	global_load_dwordx2 v[50:51], v234, s[62:63]
	s_add_u32 s62, s62, 0x1800
	s_addc_u32 s63, s63, 0
	global_load_dwordx2 v[52:53], v234, s[62:63]
	s_add_u32 s62, s62, 0x1800
	s_addc_u32 s63, s63, 0
	global_load_dwordx2 v[54:55], v234, s[62:63]
	s_add_u32 s62, s10, s39
	s_addc_u32 s63, s11, 0
	global_load_dwordx2 v[56:57], v234, s[62:63]
	s_mul_i32 s39, s55, 43
	s_add_i32 s39, s39, s56
	s_mul_i32 s39, s39, 0x1800
	s_mul_i32 s0, s37, 0x180
	s_add_i32 s39, s39, s0
	s_add_u32 s62, s30, s39
	s_addc_u32 s63, s31, 0
	global_load_dwordx4 v[0:3], v237, s[62:63] offset:0
	global_load_dwordx4 v[4:7], v237, s[62:63] offset:64
	global_load_dwordx4 v[8:11], v237, s[62:63] offset:128
	global_load_dwordx4 v[12:15], v237, s[62:63] offset:192
	global_load_dwordx4 v[16:19], v237, s[62:63] offset:256
	global_load_dwordx4 v[20:23], v237, s[62:63] offset:320
	s_mul_i32 s6, s57, 0x1800
	s_mul_hi_u32 s7, s57, 0x1800
	s_mul_i32 s39, s37, 0xc0
	s_add_u32 s6, s6, s39
	s_addc_u32 s7, s7, 0
	s_add_u32 s6, s6, s28
	s_addc_u32 s7, s7, s29
	s_mul_i32 s100, s57, 0xc00
	s_mul_hi_u32 s101, s57, 0xc00
	s_add_u32 s100, s100, s39
	s_addc_u32 s101, s101, 0
	s_add_u32 s100, s100, s34
	s_addc_u32 s101, s101, s35
	s_mov_b32 s4, 0xbfb8aa3b
	s_mov_b32 s5, 0xbd2ec3ff
	v_mov_b32_e32 v248, 0xbe1d955b
	v_mov_b32_e32 v249, 0xbee35847
	v_mov_b32_e32 v250, 0xbf75fdf0
	v_mov_b32_e32 v251, 0xbfb17218
	v_mov_b32_e32 v36, 0xbdd2d3e8
	v_mov_b32_e32 v37, 0xc0135761
	s_waitcnt vmcnt(0)
	s_cmp_eq_u32 s56, 0
	s_cbranch_scc1 .Lscan2_hzero
	v_lshlrev_b32_e32 v58, 16, v59
	v_and_b32_e32 v59, 0xffff0000, v59
	v_lshlrev_b32_e32 v60, 16, v61
	v_and_b32_e32 v61, 0xffff0000, v61
	v_lshlrev_b32_e32 v62, 16, v63
	v_and_b32_e32 v63, 0xffff0000, v63
	s_branch .Lscan2_hdone

.Lscan2_sub:
	global_load_dwordx2 v[24:25], v235, s[6:7] offset:0
	global_load_dwordx2 v[26:27], v235, s[6:7] offset:32
	global_load_dwordx2 v[28:29], v235, s[6:7] offset:64
	global_load_dwordx2 v[30:31], v235, s[6:7] offset:96
	global_load_dwordx2 v[32:33], v235, s[6:7] offset:128
	global_load_dwordx2 v[34:35], v235, s[6:7] offset:160
	s_mov_b64 s[62:63], s[44:45]
	global_load_dword v82, v233, s[62:63]
	s_add_u32 s62, s62, 0x1800
	s_addc_u32 s63, s63, 0
	global_load_dword v83, v233, s[62:63]
	s_add_u32 s62, s62, 0x1800
	s_addc_u32 s63, s63, 0
	global_load_dword v84, v233, s[62:63]
	s_add_u32 s62, s62, 0x1800
	s_addc_u32 s63, s63, 0
	global_load_dword v85, v233, s[62:63]
	s_add_u32 s62, s62, 0x1800
	s_addc_u32 s63, s63, 0
	global_load_dword v86, v233, s[62:63]
	s_add_u32 s62, s62, 0x1800
	s_addc_u32 s63, s63, 0
	global_load_dword v87, v233, s[62:63]
	s_add_u32 s62, s62, 0x1800
	s_addc_u32 s63, s63, 0
	global_load_dword v88, v233, s[62:63]
	s_add_u32 s62, s62, 0x1800
	s_addc_u32 s63, s63, 0
	global_load_dword v89, v233, s[62:63]
	s_add_u32 s62, s62, 0x1800
	s_addc_u32 s63, s63, 0
	global_load_dword v90, v233, s[62:63]
	s_add_u32 s62, s62, 0x1800
	s_addc_u32 s63, s63, 0
	global_load_dword v91, v233, s[62:63]
	s_add_u32 s62, s62, 0x1800
	s_addc_u32 s63, s63, 0
	global_load_dword v92, v233, s[62:63]
	s_add_u32 s62, s62, 0x1800
	s_addc_u32 s63, s63, 0
	global_load_dword v93, v233, s[62:63]
	s_add_u32 s62, s62, 0x1800
	s_addc_u32 s63, s63, 0
	global_load_dword v94, v233, s[62:63]
	s_add_u32 s62, s62, 0x1800
	s_addc_u32 s63, s63, 0
	global_load_dword v95, v233, s[62:63]
	s_add_u32 s62, s62, 0x1800
	s_addc_u32 s63, s63, 0
	global_load_dword v96, v233, s[62:63]
	s_add_u32 s62, s62, 0x1800
	s_addc_u32 s63, s63, 0
	global_load_dword v97, v233, s[62:63]
	s_add_u32 s62, s62, 0x1800
	s_addc_u32 s63, s63, 0
	s_mov_b64 s[44:45], s[62:63]
	ds_read_b128 v[110:113], v229 offset:0
	ds_read_b128 v[122:125], v229 offset:19968
	ds_read_b128 v[114:117], v229 offset:64
	ds_read_b128 v[126:129], v229 offset:20032
	ds_read_b128 v[118:121], v229 offset:128
	ds_read_b128 v[130:133], v229 offset:20096
	ds_read_b128 v[150:153], v230
	ds_read_b128 v[154:157], v230 offset:384
	ds_read_b128 v[158:161], v230 offset:768
	s_mov_b32 s62, -1
	s_mov_b32 s63, 0xffff
	s_mov_b64 exec, s[62:63]
	v_lshlrev_b32_e32 v64, 16, v66
	v_and_b32_e32 v65, 0xffff0000, v66
	v_pk_fma_f32 v[242:243], v[58:59], v[48:49], v[56:57]
	v_lshlrev_b32_e32 v58, 16, v67
	v_and_b32_e32 v59, 0xffff0000, v67
	v_pk_fma_f32 v[244:245], v[60:61], v[48:49], v[56:57]
	v_pk_fma_f32 v[242:243], v[60:61], v[50:51], v[242:243]
	v_pk_fma_f32 v[244:245], v[62:63], v[50:51], v[244:245]
	v_pk_fma_f32 v[242:243], v[62:63], v[52:53], v[242:243]
	v_pk_fma_f32 v[244:245], v[64:65], v[52:53], v[244:245]
	v_pk_fma_f32 v[242:243], v[64:65], v[54:55], v[242:243]
	v_pk_fma_f32 v[244:245], v[58:59], v[54:55], v[244:245]
	ds_write_b64 v226, v[242:243] offset:0
	v_cvt_pk_bf16_f32 v246, v242, v243
	ds_write_b64 v226, v[244:245] offset:400
	v_cvt_pk_bf16_f32 v247, v244, v245
	ds_write_b32 v227, v246 offset:0
	ds_write_b32 v227, v247 offset:208
	v_lshlrev_b32_e32 v60, 16, v68
	v_and_b32_e32 v61, 0xffff0000, v68
	v_pk_fma_f32 v[242:243], v[62:63], v[48:49], v[56:57]
	v_lshlrev_b32_e32 v62, 16, v69
	v_and_b32_e32 v63, 0xffff0000, v69
	v_pk_fma_f32 v[244:245], v[64:65], v[48:49], v[56:57]
	v_pk_fma_f32 v[242:243], v[64:65], v[50:51], v[242:243]
	v_pk_fma_f32 v[244:245], v[58:59], v[50:51], v[244:245]
	v_pk_fma_f32 v[242:243], v[58:59], v[52:53], v[242:243]
	v_pk_fma_f32 v[244:245], v[60:61], v[52:53], v[244:245]
	v_pk_fma_f32 v[242:243], v[60:61], v[54:55], v[242:243]
	v_pk_fma_f32 v[244:245], v[62:63], v[54:55], v[244:245]
	ds_write_b64 v226, v[242:243] offset:800
	v_cvt_pk_bf16_f32 v246, v242, v243
	ds_write_b64 v226, v[244:245] offset:1200
	v_cvt_pk_bf16_f32 v247, v244, v245
	ds_write_b32 v227, v246 offset:416
	ds_write_b32 v227, v247 offset:624
	v_lshlrev_b32_e32 v64, 16, v70
	v_and_b32_e32 v65, 0xffff0000, v70
	v_pk_fma_f32 v[242:243], v[58:59], v[48:49], v[56:57]
	v_lshlrev_b32_e32 v58, 16, v71
	v_and_b32_e32 v59, 0xffff0000, v71
	v_pk_fma_f32 v[244:245], v[60:61], v[48:49], v[56:57]
	v_pk_fma_f32 v[242:243], v[60:61], v[50:51], v[242:243]
	v_pk_fma_f32 v[244:245], v[62:63], v[50:51], v[244:245]
	v_pk_fma_f32 v[242:243], v[62:63], v[52:53], v[242:243]
	v_pk_fma_f32 v[244:245], v[64:65], v[52:53], v[244:245]
	v_pk_fma_f32 v[242:243], v[64:65], v[54:55], v[242:243]
	v_pk_fma_f32 v[244:245], v[58:59], v[54:55], v[244:245]
	ds_write_b64 v226, v[242:243] offset:1600
	v_cvt_pk_bf16_f32 v246, v242, v243
	ds_write_b64 v226, v[244:245] offset:2000
	v_cvt_pk_bf16_f32 v247, v244, v245
	ds_write_b32 v227, v246 offset:832
	ds_write_b32 v227, v247 offset:1040
	v_lshlrev_b32_e32 v60, 16, v72
	v_and_b32_e32 v61, 0xffff0000, v72
	v_pk_fma_f32 v[242:243], v[62:63], v[48:49], v[56:57]
	v_lshlrev_b32_e32 v62, 16, v73
	v_and_b32_e32 v63, 0xffff0000, v73
	v_pk_fma_f32 v[244:245], v[64:65], v[48:49], v[56:57]
	v_pk_fma_f32 v[242:243], v[64:65], v[50:51], v[242:243]
	v_pk_fma_f32 v[244:245], v[58:59], v[50:51], v[244:245]
	v_pk_fma_f32 v[242:243], v[58:59], v[52:53], v[242:243]
	v_pk_fma_f32 v[244:245], v[60:61], v[52:53], v[244:245]
	v_pk_fma_f32 v[242:243], v[60:61], v[54:55], v[242:243]
	v_pk_fma_f32 v[244:245], v[62:63], v[54:55], v[244:245]
	ds_write_b64 v226, v[242:243] offset:2400
	v_cvt_pk_bf16_f32 v246, v242, v243
	ds_write_b64 v226, v[244:245] offset:2800
	v_cvt_pk_bf16_f32 v247, v244, v245
	ds_write_b32 v227, v246 offset:1248
	ds_write_b32 v227, v247 offset:1456
	v_lshlrev_b32_e32 v64, 16, v74
	v_and_b32_e32 v65, 0xffff0000, v74
	v_pk_fma_f32 v[242:243], v[58:59], v[48:49], v[56:57]
	v_lshlrev_b32_e32 v58, 16, v75
	v_and_b32_e32 v59, 0xffff0000, v75
	v_pk_fma_f32 v[244:245], v[60:61], v[48:49], v[56:57]
	v_pk_fma_f32 v[242:243], v[60:61], v[50:51], v[242:243]
	v_pk_fma_f32 v[244:245], v[62:63], v[50:51], v[244:245]
	v_pk_fma_f32 v[242:243], v[62:63], v[52:53], v[242:243]
	v_pk_fma_f32 v[244:245], v[64:65], v[52:53], v[244:245]
	v_pk_fma_f32 v[242:243], v[64:65], v[54:55], v[242:243]
	v_pk_fma_f32 v[244:245], v[58:59], v[54:55], v[244:245]
	ds_write_b64 v226, v[242:243] offset:3200
	v_cvt_pk_bf16_f32 v246, v242, v243
	ds_write_b64 v226, v[244:245] offset:3600
	v_cvt_pk_bf16_f32 v247, v244, v245
	ds_write_b32 v227, v246 offset:1664
	ds_write_b32 v227, v247 offset:1872
	v_lshlrev_b32_e32 v60, 16, v76
	v_and_b32_e32 v61, 0xffff0000, v76
	v_pk_fma_f32 v[242:243], v[62:63], v[48:49], v[56:57]
	v_lshlrev_b32_e32 v62, 16, v77
	v_and_b32_e32 v63, 0xffff0000, v77
	v_pk_fma_f32 v[244:245], v[64:65], v[48:49], v[56:57]
	v_pk_fma_f32 v[242:243], v[64:65], v[50:51], v[242:243]
	v_pk_fma_f32 v[244:245], v[58:59], v[50:51], v[244:245]
	v_pk_fma_f32 v[242:243], v[58:59], v[52:53], v[242:243]
	v_pk_fma_f32 v[244:245], v[60:61], v[52:53], v[244:245]
	v_pk_fma_f32 v[242:243], v[60:61], v[54:55], v[242:243]
	v_pk_fma_f32 v[244:245], v[62:63], v[54:55], v[244:245]
	ds_write_b64 v226, v[242:243] offset:4000
	v_cvt_pk_bf16_f32 v246, v242, v243
	ds_write_b64 v226, v[244:245] offset:4400
	v_cvt_pk_bf16_f32 v247, v244, v245
	ds_write_b32 v227, v246 offset:2080
	ds_write_b32 v227, v247 offset:2288
	v_lshlrev_b32_e32 v64, 16, v78
	v_and_b32_e32 v65, 0xffff0000, v78
	v_pk_fma_f32 v[242:243], v[58:59], v[48:49], v[56:57]
	v_lshlrev_b32_e32 v58, 16, v79
	v_and_b32_e32 v59, 0xffff0000, v79
	v_pk_fma_f32 v[244:245], v[60:61], v[48:49], v[56:57]
	v_pk_fma_f32 v[242:243], v[60:61], v[50:51], v[242:243]
	v_pk_fma_f32 v[244:245], v[62:63], v[50:51], v[244:245]
	v_pk_fma_f32 v[242:243], v[62:63], v[52:53], v[242:243]
	v_pk_fma_f32 v[244:245], v[64:65], v[52:53], v[244:245]
	v_pk_fma_f32 v[242:243], v[64:65], v[54:55], v[242:243]
	v_pk_fma_f32 v[244:245], v[58:59], v[54:55], v[244:245]
	ds_write_b64 v226, v[242:243] offset:4800
	v_cvt_pk_bf16_f32 v246, v242, v243
	ds_write_b64 v226, v[244:245] offset:5200
	v_cvt_pk_bf16_f32 v247, v244, v245
	ds_write_b32 v227, v246 offset:2496
	ds_write_b32 v227, v247 offset:2704
	v_lshlrev_b32_e32 v60, 16, v80
	v_and_b32_e32 v61, 0xffff0000, v80
	v_pk_fma_f32 v[242:243], v[62:63], v[48:49], v[56:57]
	v_lshlrev_b32_e32 v62, 16, v81
	v_and_b32_e32 v63, 0xffff0000, v81
	v_pk_fma_f32 v[244:245], v[64:65], v[48:49], v[56:57]
	v_pk_fma_f32 v[242:243], v[64:65], v[50:51], v[242:243]
	v_pk_fma_f32 v[244:245], v[58:59], v[50:51], v[244:245]
	v_pk_fma_f32 v[242:243], v[58:59], v[52:53], v[242:243]
	v_pk_fma_f32 v[244:245], v[60:61], v[52:53], v[244:245]
	v_pk_fma_f32 v[242:243], v[60:61], v[54:55], v[242:243]
	v_pk_fma_f32 v[244:245], v[62:63], v[54:55], v[244:245]
	ds_write_b64 v226, v[242:243] offset:5600
	v_cvt_pk_bf16_f32 v246, v242, v243
	ds_write_b64 v226, v[244:245] offset:6000
	v_cvt_pk_bf16_f32 v247, v244, v245
	ds_write_b32 v227, v246 offset:2912
	ds_write_b32 v227, v247 offset:3120
	s_mov_b64 exec, -1
	s_waitcnt lgkmcnt(0)
	ds_read_b128 v[98:101], v228 offset:0
	ds_read_b128 v[102:105], v228 offset:64
	ds_read_b128 v[106:109], v228 offset:128
	ds_read_b128 v[162:165], v231
	s_waitcnt lgkmcnt(0)
	v_mfma_f32_16x16x32_bf16 v[134:137], v[110:113], v[98:101], 0
	v_mfma_f32_16x16x32_bf16 v[138:141], v[122:125], v[98:101], 0
	v_mfma_f32_16x16x32_bf16 v[134:137], v[114:117], v[102:105], v[134:137]
	v_mfma_f32_16x16x32_bf16 v[138:141], v[126:129], v[102:105], v[138:141]
	v_mfma_f32_16x16x32_bf16 v[134:137], v[118:121], v[106:109], v[134:137]
	v_mfma_f32_16x16x32_bf16 v[138:141], v[130:133], v[106:109], v[138:141]
	ds_read_b128 v[110:113], v229 offset:3328
	ds_read_b128 v[122:125], v229 offset:23296
	ds_read_b128 v[114:117], v229 offset:3392
	ds_read_b128 v[126:129], v229 offset:23360
	ds_read_b128 v[118:121], v229 offset:3456
	ds_read_b128 v[130:133], v229 offset:23424
	s_nop 7
	s_nop 7
	v_pk_fma_f32 v[166:167], v[134:135], s[4:5], v[150:151] op_sel_hi:[1,0,1]
	v_pk_fma_f32 v[168:169], v[136:137], s[4:5], v[152:153] op_sel_hi:[1,0,1]
	v_pk_fma_f32 v[204:205], v[138:139], s[4:5], v[154:155] op_sel_hi:[1,0,1]
	v_pk_fma_f32 v[206:207], v[140:141], s[4:5], v[156:157] op_sel_hi:[1,0,1]
	v_exp_f32_e32 v166, v166
	v_exp_f32_e32 v167, v167
	v_exp_f32_e32 v168, v168
	v_exp_f32_e32 v169, v169
	v_exp_f32_e32 v204, v204
	v_exp_f32_e32 v205, v205
	v_exp_f32_e32 v206, v206
	v_exp_f32_e32 v207, v207
	v_pk_add_f32 v[166:167], v[166:167], 1.0 op_sel_hi:[1,0]
	v_pk_add_f32 v[168:169], v[168:169], 1.0 op_sel_hi:[1,0]
	v_pk_add_f32 v[204:205], v[204:205], 1.0 op_sel_hi:[1,0]
	v_pk_add_f32 v[206:207], v[206:207], 1.0 op_sel_hi:[1,0]
	v_rcp_f32_e32 v166, v166
	v_rcp_f32_e32 v167, v167
	v_rcp_f32_e32 v168, v168
	v_rcp_f32_e32 v169, v169
	v_rcp_f32_e32 v204, v204
	v_rcp_f32_e32 v205, v205
	v_rcp_f32_e32 v206, v206
	v_rcp_f32_e32 v207, v207
	v_pk_mul_f32 v[208:209], v[158:159], v[166:167]
	v_pk_mul_f32 v[210:211], v[160:161], v[168:169]
	v_pk_mul_f32 v[204:205], v[162:163], v[204:205]
	v_pk_mul_f32 v[206:207], v[164:165], v[206:207]
	ds_read_b128 v[150:153], v230 offset:64
	ds_read_b128 v[154:157], v230 offset:448
	ds_read_b128 v[158:161], v230 offset:832
	ds_read_b128 v[162:165], v231 offset:64
	v_exp_f32_e32 v166, v208
	v_exp_f32_e32 v167, v209
	v_exp_f32_e32 v168, v210
	v_exp_f32_e32 v169, v211
	v_pk_fma_f32 v[216:217], v[208:209], s[4:5], v[248:249] op_sel:[0,1,0] op_sel_hi:[1,1,0]
	v_pk_fma_f32 v[218:219], v[210:211], s[4:5], v[248:249] op_sel:[0,1,0] op_sel_hi:[1,1,0]
	v_pk_fma_f32 v[216:217], v[208:209], v[216:217], v[248:249] op_sel:[0,0,1] op_sel_hi:[1,1,1]
	v_pk_fma_f32 v[218:219], v[210:211], v[218:219], v[248:249] op_sel:[0,0,1] op_sel_hi:[1,1,1]
	v_min3_f32 v212, v208, v209, v210
	v_pk_fma_f32 v[216:217], v[208:209], v[216:217], v[250:251] op_sel_hi:[1,1,0]
	v_pk_fma_f32 v[218:219], v[210:211], v[218:219], v[250:251] op_sel_hi:[1,1,0]
	v_min_f32_e32 v212, v212, v211
	v_pk_fma_f32 v[216:217], v[208:209], v[216:217], v[250:251] op_sel:[0,0,1] op_sel_hi:[1,1,1]
	v_pk_fma_f32 v[218:219], v[210:211], v[218:219], v[250:251] op_sel:[0,0,1] op_sel_hi:[1,1,1]
	v_cmp_nlt_f32_e32 vcc, 0xbe38aa3b, v212
	v_pk_mul_f32 v[216:217], v[216:217], v[208:209]
	v_pk_mul_f32 v[218:219], v[218:219], v[210:211]
	s_cbranch_vccnz .Lscan2_far0
.Lscan2_back0:
	v_sqrt_f32_e32 v216, v216
	v_sqrt_f32_e32 v217, v217
	v_sqrt_f32_e32 v218, v218
	v_sqrt_f32_e32 v219, v219
	v_pk_mul_f32 v[204:205], v[204:205], v[216:217]
	v_pk_mul_f32 v[206:207], v[206:207], v[218:219]
	s_waitcnt lgkmcnt(0)
	v_mfma_f32_16x16x32_bf16 v[142:145], v[110:113], v[98:101], 0
	v_mfma_f32_16x16x32_bf16 v[146:149], v[122:125], v[98:101], 0
	v_mfma_f32_16x16x32_bf16 v[142:145], v[114:117], v[102:105], v[142:145]
	v_mfma_f32_16x16x32_bf16 v[146:149], v[126:129], v[102:105], v[146:149]
	v_mfma_f32_16x16x32_bf16 v[142:145], v[118:121], v[106:109], v[142:145]
	v_mfma_f32_16x16x32_bf16 v[146:149], v[130:133], v[106:109], v[146:149]
	s_nop 1
	v_fmac_f32_dpp v204, v204, v166 row_shr:1 row_mask:0xf bank_mask:0xf bound_ctrl:1
	v_fmac_f32_dpp v205, v205, v167 row_shr:1 row_mask:0xf bank_mask:0xf bound_ctrl:1
	v_fmac_f32_dpp v206, v206, v168 row_shr:1 row_mask:0xf bank_mask:0xf bound_ctrl:1
	v_fmac_f32_dpp v207, v207, v169 row_shr:1 row_mask:0xf bank_mask:0xf bound_ctrl:1
	v_mul_f32_dpp v166, v166, v166 row_shr:1 row_mask:0xf bank_mask:0xf
	v_mul_f32_dpp v167, v167, v167 row_shr:1 row_mask:0xf bank_mask:0xf
	v_mul_f32_dpp v168, v168, v168 row_shr:1 row_mask:0xf bank_mask:0xf
	v_mul_f32_dpp v169, v169, v169 row_shr:1 row_mask:0xf bank_mask:0xf
	v_fmac_f32_dpp v204, v204, v166 row_shr:2 row_mask:0xf bank_mask:0xf bound_ctrl:1
	v_fmac_f32_dpp v205, v205, v167 row_shr:2 row_mask:0xf bank_mask:0xf bound_ctrl:1
	v_fmac_f32_dpp v206, v206, v168 row_shr:2 row_mask:0xf bank_mask:0xf bound_ctrl:1
	v_fmac_f32_dpp v207, v207, v169 row_shr:2 row_mask:0xf bank_mask:0xf bound_ctrl:1
	v_mul_f32_dpp v166, v166, v166 row_shr:2 row_mask:0xf bank_mask:0xf
	v_mul_f32_dpp v167, v167, v167 row_shr:2 row_mask:0xf bank_mask:0xf
	v_mul_f32_dpp v168, v168, v168 row_shr:2 row_mask:0xf bank_mask:0xf
	v_mul_f32_dpp v169, v169, v169 row_shr:2 row_mask:0xf bank_mask:0xf
	v_fmac_f32_dpp v204, v204, v166 row_shr:4 row_mask:0xf bank_mask:0xf bound_ctrl:1
	v_fmac_f32_dpp v205, v205, v167 row_shr:4 row_mask:0xf bank_mask:0xf bound_ctrl:1
	v_fmac_f32_dpp v206, v206, v168 row_shr:4 row_mask:0xf bank_mask:0xf bound_ctrl:1
	v_fmac_f32_dpp v207, v207, v169 row_shr:4 row_mask:0xf bank_mask:0xf bound_ctrl:1
	v_mul_f32_dpp v166, v166, v166 row_shr:4 row_mask:0xf bank_mask:0xf
	v_mul_f32_dpp v167, v167, v167 row_shr:4 row_mask:0xf bank_mask:0xf
	v_mul_f32_dpp v168, v168, v168 row_shr:4 row_mask:0xf bank_mask:0xf
	v_mul_f32_dpp v169, v169, v169 row_shr:4 row_mask:0xf bank_mask:0xf
	v_fmac_f32_dpp v204, v204, v166 row_shr:8 row_mask:0xf bank_mask:0xf bound_ctrl:1
	v_fmac_f32_dpp v205, v205, v167 row_shr:8 row_mask:0xf bank_mask:0xf bound_ctrl:1
	v_fmac_f32_dpp v206, v206, v168 row_shr:8 row_mask:0xf bank_mask:0xf bound_ctrl:1
	v_fmac_f32_dpp v207, v207, v169 row_shr:8 row_mask:0xf bank_mask:0xf bound_ctrl:1
	v_mul_f32_dpp v166, v166, v166 row_shr:8 row_mask:0xf bank_mask:0xf
	v_mul_f32_dpp v167, v167, v167 row_shr:8 row_mask:0xf bank_mask:0xf
	v_mul_f32_dpp v168, v168, v168 row_shr:8 row_mask:0xf bank_mask:0xf
	v_mul_f32_dpp v169, v169, v169 row_shr:8 row_mask:0xf bank_mask:0xf
	v_fma_f32 v208, v166, v0, v204
	v_fma_f32 v209, v167, v1, v205
	v_fma_f32 v210, v168, v2, v206
	v_fma_f32 v211, v169, v3, v207
	ds_bpermute_b32 v0, v232, v208
	ds_bpermute_b32 v1, v232, v209
	ds_bpermute_b32 v2, v232, v210
	ds_bpermute_b32 v3, v232, v211
	s_waitcnt vmcnt(21)
	v_lshlrev_b32_e32 v212, 16, v24
	v_and_b32_e32 v213, 0xffff0000, v24
	v_lshlrev_b32_e32 v214, 16, v25
	v_and_b32_e32 v215, 0xffff0000, v25
	v_pk_mul_f32 v[216:217], v[212:213], v[212:213]
	v_pk_mul_f32 v[218:219], v[214:215], v[214:215]
	v_pk_fma_f32 v[216:217], v[216:217], v[36:37], v[36:37] op_sel:[0,0,1] op_sel_hi:[1,0,1]
	v_pk_fma_f32 v[218:219], v[218:219], v[36:37], v[36:37] op_sel:[0,0,1] op_sel_hi:[1,0,1]
	v_pk_mul_f32 v[216:217], v[212:213], v[216:217]
	v_pk_mul_f32 v[218:219], v[214:215], v[218:219]
	v_exp_f32_e32 v216, v216
	v_exp_f32_e32 v217, v217
	v_exp_f32_e32 v218, v218
	v_exp_f32_e32 v219, v219
	v_pk_add_f32 v[216:217], v[216:217], 1.0 op_sel_hi:[1,0]
	v_pk_add_f32 v[218:219], v[218:219], 1.0 op_sel_hi:[1,0]
	v_rcp_f32_e32 v216, v216
	v_rcp_f32_e32 v217, v217
	v_rcp_f32_e32 v218, v218
	v_rcp_f32_e32 v219, v219
	v_pk_mul_f32 v[216:217], v[212:213], v[216:217]
	v_pk_mul_f32 v[218:219], v[214:215], v[218:219]
	v_pk_mul_f32 v[216:217], v[216:217], v[208:209]
	v_pk_mul_f32 v[218:219], v[218:219], v[210:211]
	v_cvt_pk_bf16_f32 v242, v216, v217
	v_cvt_pk_bf16_f32 v243, v218, v219
	global_store_dwordx2 v236, v[242:243], s[100:101] offset:0
	ds_read_b128 v[110:113], v229 offset:6656
	ds_read_b128 v[122:125], v229 offset:26624
	ds_read_b128 v[114:117], v229 offset:6720
	ds_read_b128 v[126:129], v229 offset:26688
	ds_read_b128 v[118:121], v229 offset:6784
	ds_read_b128 v[130:133], v229 offset:26752
	v_pk_fma_f32 v[166:167], v[142:143], s[4:5], v[150:151] op_sel_hi:[1,0,1]
	v_pk_fma_f32 v[168:169], v[144:145], s[4:5], v[152:153] op_sel_hi:[1,0,1]
	v_pk_fma_f32 v[204:205], v[146:147], s[4:5], v[154:155] op_sel_hi:[1,0,1]
	v_pk_fma_f32 v[206:207], v[148:149], s[4:5], v[156:157] op_sel_hi:[1,0,1]
	v_exp_f32_e32 v166, v166
	v_exp_f32_e32 v167, v167
	v_exp_f32_e32 v168, v168
	v_exp_f32_e32 v169, v169
	v_exp_f32_e32 v204, v204
	v_exp_f32_e32 v205, v205
	v_exp_f32_e32 v206, v206
	v_exp_f32_e32 v207, v207
	v_pk_add_f32 v[166:167], v[166:167], 1.0 op_sel_hi:[1,0]
	v_pk_add_f32 v[168:169], v[168:169], 1.0 op_sel_hi:[1,0]
	v_pk_add_f32 v[204:205], v[204:205], 1.0 op_sel_hi:[1,0]
	v_pk_add_f32 v[206:207], v[206:207], 1.0 op_sel_hi:[1,0]
	v_rcp_f32_e32 v166, v166
	v_rcp_f32_e32 v167, v167
	v_rcp_f32_e32 v168, v168
	v_rcp_f32_e32 v169, v169
	v_rcp_f32_e32 v204, v204
	v_rcp_f32_e32 v205, v205
	v_rcp_f32_e32 v206, v206
	v_rcp_f32_e32 v207, v207
	v_pk_mul_f32 v[208:209], v[158:159], v[166:167]
	v_pk_mul_f32 v[210:211], v[160:161], v[168:169]
	v_pk_mul_f32 v[204:205], v[162:163], v[204:205]
	v_pk_mul_f32 v[206:207], v[164:165], v[206:207]
	ds_read_b128 v[150:153], v230 offset:128
	ds_read_b128 v[154:157], v230 offset:512
	ds_read_b128 v[158:161], v230 offset:896
	ds_read_b128 v[162:165], v231 offset:128
	v_exp_f32_e32 v166, v208
	v_exp_f32_e32 v167, v209
	v_exp_f32_e32 v168, v210
	v_exp_f32_e32 v169, v211
	v_pk_fma_f32 v[216:217], v[208:209], s[4:5], v[248:249] op_sel:[0,1,0] op_sel_hi:[1,1,0]
	v_pk_fma_f32 v[218:219], v[210:211], s[4:5], v[248:249] op_sel:[0,1,0] op_sel_hi:[1,1,0]
	v_pk_fma_f32 v[216:217], v[208:209], v[216:217], v[248:249] op_sel:[0,0,1] op_sel_hi:[1,1,1]
	v_pk_fma_f32 v[218:219], v[210:211], v[218:219], v[248:249] op_sel:[0,0,1] op_sel_hi:[1,1,1]
	v_min3_f32 v212, v208, v209, v210
	v_pk_fma_f32 v[216:217], v[208:209], v[216:217], v[250:251] op_sel_hi:[1,1,0]
	v_pk_fma_f32 v[218:219], v[210:211], v[218:219], v[250:251] op_sel_hi:[1,1,0]
	v_min_f32_e32 v212, v212, v211
	v_pk_fma_f32 v[216:217], v[208:209], v[216:217], v[250:251] op_sel:[0,0,1] op_sel_hi:[1,1,1]
	v_pk_fma_f32 v[218:219], v[210:211], v[218:219], v[250:251] op_sel:[0,0,1] op_sel_hi:[1,1,1]
	v_cmp_nlt_f32_e32 vcc, 0xbe38aa3b, v212
	v_pk_mul_f32 v[216:217], v[216:217], v[208:209]
	v_pk_mul_f32 v[218:219], v[218:219], v[210:211]
	s_cbranch_vccnz .Lscan2_far1
.Lscan2_back1:
	v_sqrt_f32_e32 v216, v216
	v_sqrt_f32_e32 v217, v217
	v_sqrt_f32_e32 v218, v218
	v_sqrt_f32_e32 v219, v219
	v_pk_mul_f32 v[204:205], v[204:205], v[216:217]
	v_pk_mul_f32 v[206:207], v[206:207], v[218:219]
	s_waitcnt lgkmcnt(0)
	v_mfma_f32_16x16x32_bf16 v[134:137], v[110:113], v[98:101], 0
	v_mfma_f32_16x16x32_bf16 v[138:141], v[122:125], v[98:101], 0
	v_mfma_f32_16x16x32_bf16 v[134:137], v[114:117], v[102:105], v[134:137]
	v_mfma_f32_16x16x32_bf16 v[138:141], v[126:129], v[102:105], v[138:141]
	v_mfma_f32_16x16x32_bf16 v[134:137], v[118:121], v[106:109], v[134:137]
	v_mfma_f32_16x16x32_bf16 v[138:141], v[130:133], v[106:109], v[138:141]
	s_nop 1
	v_fmac_f32_dpp v204, v204, v166 row_shr:1 row_mask:0xf bank_mask:0xf bound_ctrl:1
	v_fmac_f32_dpp v205, v205, v167 row_shr:1 row_mask:0xf bank_mask:0xf bound_ctrl:1
	v_fmac_f32_dpp v206, v206, v168 row_shr:1 row_mask:0xf bank_mask:0xf bound_ctrl:1
	v_fmac_f32_dpp v207, v207, v169 row_shr:1 row_mask:0xf bank_mask:0xf bound_ctrl:1
	v_mul_f32_dpp v166, v166, v166 row_shr:1 row_mask:0xf bank_mask:0xf
	v_mul_f32_dpp v167, v167, v167 row_shr:1 row_mask:0xf bank_mask:0xf
	v_mul_f32_dpp v168, v168, v168 row_shr:1 row_mask:0xf bank_mask:0xf
	v_mul_f32_dpp v169, v169, v169 row_shr:1 row_mask:0xf bank_mask:0xf
	v_fmac_f32_dpp v204, v204, v166 row_shr:2 row_mask:0xf bank_mask:0xf bound_ctrl:1
	v_fmac_f32_dpp v205, v205, v167 row_shr:2 row_mask:0xf bank_mask:0xf bound_ctrl:1
	v_fmac_f32_dpp v206, v206, v168 row_shr:2 row_mask:0xf bank_mask:0xf bound_ctrl:1
	v_fmac_f32_dpp v207, v207, v169 row_shr:2 row_mask:0xf bank_mask:0xf bound_ctrl:1
	v_mul_f32_dpp v166, v166, v166 row_shr:2 row_mask:0xf bank_mask:0xf
	v_mul_f32_dpp v167, v167, v167 row_shr:2 row_mask:0xf bank_mask:0xf
	v_mul_f32_dpp v168, v168, v168 row_shr:2 row_mask:0xf bank_mask:0xf
	v_mul_f32_dpp v169, v169, v169 row_shr:2 row_mask:0xf bank_mask:0xf
	v_fmac_f32_dpp v204, v204, v166 row_shr:4 row_mask:0xf bank_mask:0xf bound_ctrl:1
	v_fmac_f32_dpp v205, v205, v167 row_shr:4 row_mask:0xf bank_mask:0xf bound_ctrl:1
	v_fmac_f32_dpp v206, v206, v168 row_shr:4 row_mask:0xf bank_mask:0xf bound_ctrl:1
	v_fmac_f32_dpp v207, v207, v169 row_shr:4 row_mask:0xf bank_mask:0xf bound_ctrl:1
	v_mul_f32_dpp v166, v166, v166 row_shr:4 row_mask:0xf bank_mask:0xf
	v_mul_f32_dpp v167, v167, v167 row_shr:4 row_mask:0xf bank_mask:0xf
	v_mul_f32_dpp v168, v168, v168 row_shr:4 row_mask:0xf bank_mask:0xf
	v_mul_f32_dpp v169, v169, v169 row_shr:4 row_mask:0xf bank_mask:0xf
	v_fmac_f32_dpp v204, v204, v166 row_shr:8 row_mask:0xf bank_mask:0xf bound_ctrl:1
	v_fmac_f32_dpp v205, v205, v167 row_shr:8 row_mask:0xf bank_mask:0xf bound_ctrl:1
	v_fmac_f32_dpp v206, v206, v168 row_shr:8 row_mask:0xf bank_mask:0xf bound_ctrl:1
	v_fmac_f32_dpp v207, v207, v169 row_shr:8 row_mask:0xf bank_mask:0xf bound_ctrl:1
	v_mul_f32_dpp v166, v166, v166 row_shr:8 row_mask:0xf bank_mask:0xf
	v_mul_f32_dpp v167, v167, v167 row_shr:8 row_mask:0xf bank_mask:0xf
	v_mul_f32_dpp v168, v168, v168 row_shr:8 row_mask:0xf bank_mask:0xf
	v_mul_f32_dpp v169, v169, v169 row_shr:8 row_mask:0xf bank_mask:0xf
	v_fma_f32 v208, v166, v4, v204
	v_fma_f32 v209, v167, v5, v205
	v_fma_f32 v210, v168, v6, v206
	v_fma_f32 v211, v169, v7, v207
	ds_bpermute_b32 v4, v232, v208
	ds_bpermute_b32 v5, v232, v209
	ds_bpermute_b32 v6, v232, v210
	ds_bpermute_b32 v7, v232, v211
	s_waitcnt vmcnt(21)
	v_lshlrev_b32_e32 v212, 16, v26
	v_and_b32_e32 v213, 0xffff0000, v26
	v_lshlrev_b32_e32 v214, 16, v27
	v_and_b32_e32 v215, 0xffff0000, v27
	v_pk_mul_f32 v[216:217], v[212:213], v[212:213]
	v_pk_mul_f32 v[218:219], v[214:215], v[214:215]
	v_pk_fma_f32 v[216:217], v[216:217], v[36:37], v[36:37] op_sel:[0,0,1] op_sel_hi:[1,0,1]
	v_pk_fma_f32 v[218:219], v[218:219], v[36:37], v[36:37] op_sel:[0,0,1] op_sel_hi:[1,0,1]
	v_pk_mul_f32 v[216:217], v[212:213], v[216:217]
	v_pk_mul_f32 v[218:219], v[214:215], v[218:219]
	v_exp_f32_e32 v216, v216
	v_exp_f32_e32 v217, v217
	v_exp_f32_e32 v218, v218
	v_exp_f32_e32 v219, v219
	v_pk_add_f32 v[216:217], v[216:217], 1.0 op_sel_hi:[1,0]
	v_pk_add_f32 v[218:219], v[218:219], 1.0 op_sel_hi:[1,0]
	v_rcp_f32_e32 v216, v216
	v_rcp_f32_e32 v217, v217
	v_rcp_f32_e32 v218, v218
	v_rcp_f32_e32 v219, v219
	v_pk_mul_f32 v[216:217], v[212:213], v[216:217]
	v_pk_mul_f32 v[218:219], v[214:215], v[218:219]
	v_pk_mul_f32 v[216:217], v[216:217], v[208:209]
	v_pk_mul_f32 v[218:219], v[218:219], v[210:211]
	v_cvt_pk_bf16_f32 v242, v216, v217
	v_cvt_pk_bf16_f32 v243, v218, v219
	global_store_dwordx2 v236, v[242:243], s[100:101] offset:32
	ds_read_b128 v[110:113], v229 offset:9984
	ds_read_b128 v[122:125], v229 offset:29952
	ds_read_b128 v[114:117], v229 offset:10048
	ds_read_b128 v[126:129], v229 offset:30016
	ds_read_b128 v[118:121], v229 offset:10112
	ds_read_b128 v[130:133], v229 offset:30080
	v_pk_fma_f32 v[166:167], v[134:135], s[4:5], v[150:151] op_sel_hi:[1,0,1]
	v_pk_fma_f32 v[168:169], v[136:137], s[4:5], v[152:153] op_sel_hi:[1,0,1]
	v_pk_fma_f32 v[204:205], v[138:139], s[4:5], v[154:155] op_sel_hi:[1,0,1]
	v_pk_fma_f32 v[206:207], v[140:141], s[4:5], v[156:157] op_sel_hi:[1,0,1]
	v_exp_f32_e32 v166, v166
	v_exp_f32_e32 v167, v167
	v_exp_f32_e32 v168, v168
	v_exp_f32_e32 v169, v169
	v_exp_f32_e32 v204, v204
	v_exp_f32_e32 v205, v205
	v_exp_f32_e32 v206, v206
	v_exp_f32_e32 v207, v207
	v_pk_add_f32 v[166:167], v[166:167], 1.0 op_sel_hi:[1,0]
	v_pk_add_f32 v[168:169], v[168:169], 1.0 op_sel_hi:[1,0]
	v_pk_add_f32 v[204:205], v[204:205], 1.0 op_sel_hi:[1,0]
	v_pk_add_f32 v[206:207], v[206:207], 1.0 op_sel_hi:[1,0]
	v_rcp_f32_e32 v166, v166
	v_rcp_f32_e32 v167, v167
	v_rcp_f32_e32 v168, v168
	v_rcp_f32_e32 v169, v169
	v_rcp_f32_e32 v204, v204
	v_rcp_f32_e32 v205, v205
	v_rcp_f32_e32 v206, v206
	v_rcp_f32_e32 v207, v207
	v_pk_mul_f32 v[208:209], v[158:159], v[166:167]
	v_pk_mul_f32 v[210:211], v[160:161], v[168:169]
	v_pk_mul_f32 v[204:205], v[162:163], v[204:205]
	v_pk_mul_f32 v[206:207], v[164:165], v[206:207]
	ds_read_b128 v[150:153], v230 offset:192
	ds_read_b128 v[154:157], v230 offset:576
	ds_read_b128 v[158:161], v230 offset:960
	ds_read_b128 v[162:165], v231 offset:192
	v_exp_f32_e32 v166, v208
	v_exp_f32_e32 v167, v209
	v_exp_f32_e32 v168, v210
	v_exp_f32_e32 v169, v211
	v_pk_fma_f32 v[216:217], v[208:209], s[4:5], v[248:249] op_sel:[0,1,0] op_sel_hi:[1,1,0]
	v_pk_fma_f32 v[218:219], v[210:211], s[4:5], v[248:249] op_sel:[0,1,0] op_sel_hi:[1,1,0]
	v_pk_fma_f32 v[216:217], v[208:209], v[216:217], v[248:249] op_sel:[0,0,1] op_sel_hi:[1,1,1]
	v_pk_fma_f32 v[218:219], v[210:211], v[218:219], v[248:249] op_sel:[0,0,1] op_sel_hi:[1,1,1]
	v_min3_f32 v212, v208, v209, v210
	v_pk_fma_f32 v[216:217], v[208:209], v[216:217], v[250:251] op_sel_hi:[1,1,0]
	v_pk_fma_f32 v[218:219], v[210:211], v[218:219], v[250:251] op_sel_hi:[1,1,0]
	v_min_f32_e32 v212, v212, v211
	v_pk_fma_f32 v[216:217], v[208:209], v[216:217], v[250:251] op_sel:[0,0,1] op_sel_hi:[1,1,1]
	v_pk_fma_f32 v[218:219], v[210:211], v[218:219], v[250:251] op_sel:[0,0,1] op_sel_hi:[1,1,1]
	v_cmp_nlt_f32_e32 vcc, 0xbe38aa3b, v212
	v_pk_mul_f32 v[216:217], v[216:217], v[208:209]
	v_pk_mul_f32 v[218:219], v[218:219], v[210:211]
	s_cbranch_vccnz .Lscan2_far2
.Lscan2_back2:
	v_sqrt_f32_e32 v216, v216
	v_sqrt_f32_e32 v217, v217
	v_sqrt_f32_e32 v218, v218
	v_sqrt_f32_e32 v219, v219
	v_pk_mul_f32 v[204:205], v[204:205], v[216:217]
	v_pk_mul_f32 v[206:207], v[206:207], v[218:219]
	s_waitcnt lgkmcnt(0)
	v_mfma_f32_16x16x32_bf16 v[142:145], v[110:113], v[98:101], 0
	v_mfma_f32_16x16x32_bf16 v[146:149], v[122:125], v[98:101], 0
	v_mfma_f32_16x16x32_bf16 v[142:145], v[114:117], v[102:105], v[142:145]
	v_mfma_f32_16x16x32_bf16 v[146:149], v[126:129], v[102:105], v[146:149]
	v_mfma_f32_16x16x32_bf16 v[142:145], v[118:121], v[106:109], v[142:145]
	v_mfma_f32_16x16x32_bf16 v[146:149], v[130:133], v[106:109], v[146:149]
	s_nop 1
	v_fmac_f32_dpp v204, v204, v166 row_shr:1 row_mask:0xf bank_mask:0xf bound_ctrl:1
	v_fmac_f32_dpp v205, v205, v167 row_shr:1 row_mask:0xf bank_mask:0xf bound_ctrl:1
	v_fmac_f32_dpp v206, v206, v168 row_shr:1 row_mask:0xf bank_mask:0xf bound_ctrl:1
	v_fmac_f32_dpp v207, v207, v169 row_shr:1 row_mask:0xf bank_mask:0xf bound_ctrl:1
	v_mul_f32_dpp v166, v166, v166 row_shr:1 row_mask:0xf bank_mask:0xf
	v_mul_f32_dpp v167, v167, v167 row_shr:1 row_mask:0xf bank_mask:0xf
	v_mul_f32_dpp v168, v168, v168 row_shr:1 row_mask:0xf bank_mask:0xf
	v_mul_f32_dpp v169, v169, v169 row_shr:1 row_mask:0xf bank_mask:0xf
	v_fmac_f32_dpp v204, v204, v166 row_shr:2 row_mask:0xf bank_mask:0xf bound_ctrl:1
	v_fmac_f32_dpp v205, v205, v167 row_shr:2 row_mask:0xf bank_mask:0xf bound_ctrl:1
	v_fmac_f32_dpp v206, v206, v168 row_shr:2 row_mask:0xf bank_mask:0xf bound_ctrl:1
	v_fmac_f32_dpp v207, v207, v169 row_shr:2 row_mask:0xf bank_mask:0xf bound_ctrl:1
	v_mul_f32_dpp v166, v166, v166 row_shr:2 row_mask:0xf bank_mask:0xf
	v_mul_f32_dpp v167, v167, v167 row_shr:2 row_mask:0xf bank_mask:0xf
	v_mul_f32_dpp v168, v168, v168 row_shr:2 row_mask:0xf bank_mask:0xf
	v_mul_f32_dpp v169, v169, v169 row_shr:2 row_mask:0xf bank_mask:0xf
	v_fmac_f32_dpp v204, v204, v166 row_shr:4 row_mask:0xf bank_mask:0xf bound_ctrl:1
	v_fmac_f32_dpp v205, v205, v167 row_shr:4 row_mask:0xf bank_mask:0xf bound_ctrl:1
	v_fmac_f32_dpp v206, v206, v168 row_shr:4 row_mask:0xf bank_mask:0xf bound_ctrl:1
	v_fmac_f32_dpp v207, v207, v169 row_shr:4 row_mask:0xf bank_mask:0xf bound_ctrl:1
	v_mul_f32_dpp v166, v166, v166 row_shr:4 row_mask:0xf bank_mask:0xf
	v_mul_f32_dpp v167, v167, v167 row_shr:4 row_mask:0xf bank_mask:0xf
	v_mul_f32_dpp v168, v168, v168 row_shr:4 row_mask:0xf bank_mask:0xf
	v_mul_f32_dpp v169, v169, v169 row_shr:4 row_mask:0xf bank_mask:0xf
	v_fmac_f32_dpp v204, v204, v166 row_shr:8 row_mask:0xf bank_mask:0xf bound_ctrl:1
	v_fmac_f32_dpp v205, v205, v167 row_shr:8 row_mask:0xf bank_mask:0xf bound_ctrl:1
	v_fmac_f32_dpp v206, v206, v168 row_shr:8 row_mask:0xf bank_mask:0xf bound_ctrl:1
	v_fmac_f32_dpp v207, v207, v169 row_shr:8 row_mask:0xf bank_mask:0xf bound_ctrl:1
	v_mul_f32_dpp v166, v166, v166 row_shr:8 row_mask:0xf bank_mask:0xf
	v_mul_f32_dpp v167, v167, v167 row_shr:8 row_mask:0xf bank_mask:0xf
	v_mul_f32_dpp v168, v168, v168 row_shr:8 row_mask:0xf bank_mask:0xf
	v_mul_f32_dpp v169, v169, v169 row_shr:8 row_mask:0xf bank_mask:0xf
	v_fma_f32 v208, v166, v8, v204
	v_fma_f32 v209, v167, v9, v205
	v_fma_f32 v210, v168, v10, v206
	v_fma_f32 v211, v169, v11, v207
	ds_bpermute_b32 v8, v232, v208
	ds_bpermute_b32 v9, v232, v209
	ds_bpermute_b32 v10, v232, v210
	ds_bpermute_b32 v11, v232, v211
	s_waitcnt vmcnt(21)
	v_lshlrev_b32_e32 v212, 16, v28
	v_and_b32_e32 v213, 0xffff0000, v28
	v_lshlrev_b32_e32 v214, 16, v29
	v_and_b32_e32 v215, 0xffff0000, v29
	v_pk_mul_f32 v[216:217], v[212:213], v[212:213]
	v_pk_mul_f32 v[218:219], v[214:215], v[214:215]
	v_pk_fma_f32 v[216:217], v[216:217], v[36:37], v[36:37] op_sel:[0,0,1] op_sel_hi:[1,0,1]
	v_pk_fma_f32 v[218:219], v[218:219], v[36:37], v[36:37] op_sel:[0,0,1] op_sel_hi:[1,0,1]
	v_pk_mul_f32 v[216:217], v[212:213], v[216:217]
	v_pk_mul_f32 v[218:219], v[214:215], v[218:219]
	v_exp_f32_e32 v216, v216
	v_exp_f32_e32 v217, v217
	v_exp_f32_e32 v218, v218
	v_exp_f32_e32 v219, v219
	v_pk_add_f32 v[216:217], v[216:217], 1.0 op_sel_hi:[1,0]
	v_pk_add_f32 v[218:219], v[218:219], 1.0 op_sel_hi:[1,0]
	v_rcp_f32_e32 v216, v216
	v_rcp_f32_e32 v217, v217
	v_rcp_f32_e32 v218, v218
	v_rcp_f32_e32 v219, v219
	v_pk_mul_f32 v[216:217], v[212:213], v[216:217]
	v_pk_mul_f32 v[218:219], v[214:215], v[218:219]
	v_pk_mul_f32 v[216:217], v[216:217], v[208:209]
	v_pk_mul_f32 v[218:219], v[218:219], v[210:211]
	v_cvt_pk_bf16_f32 v242, v216, v217
	v_cvt_pk_bf16_f32 v243, v218, v219
	global_store_dwordx2 v236, v[242:243], s[100:101] offset:64
	ds_read_b128 v[110:113], v229 offset:13312
	ds_read_b128 v[122:125], v229 offset:33280
	ds_read_b128 v[114:117], v229 offset:13376
	ds_read_b128 v[126:129], v229 offset:33344
	ds_read_b128 v[118:121], v229 offset:13440
	ds_read_b128 v[130:133], v229 offset:33408
	v_pk_fma_f32 v[166:167], v[142:143], s[4:5], v[150:151] op_sel_hi:[1,0,1]
	v_pk_fma_f32 v[168:169], v[144:145], s[4:5], v[152:153] op_sel_hi:[1,0,1]
	v_pk_fma_f32 v[204:205], v[146:147], s[4:5], v[154:155] op_sel_hi:[1,0,1]
	v_pk_fma_f32 v[206:207], v[148:149], s[4:5], v[156:157] op_sel_hi:[1,0,1]
	v_exp_f32_e32 v166, v166
	v_exp_f32_e32 v167, v167
	v_exp_f32_e32 v168, v168
	v_exp_f32_e32 v169, v169
	v_exp_f32_e32 v204, v204
	v_exp_f32_e32 v205, v205
	v_exp_f32_e32 v206, v206
	v_exp_f32_e32 v207, v207
	v_pk_add_f32 v[166:167], v[166:167], 1.0 op_sel_hi:[1,0]
	v_pk_add_f32 v[168:169], v[168:169], 1.0 op_sel_hi:[1,0]
	v_pk_add_f32 v[204:205], v[204:205], 1.0 op_sel_hi:[1,0]
	v_pk_add_f32 v[206:207], v[206:207], 1.0 op_sel_hi:[1,0]
	v_rcp_f32_e32 v166, v166
	v_rcp_f32_e32 v167, v167
	v_rcp_f32_e32 v168, v168
	v_rcp_f32_e32 v169, v169
	v_rcp_f32_e32 v204, v204
	v_rcp_f32_e32 v205, v205
	v_rcp_f32_e32 v206, v206
	v_rcp_f32_e32 v207, v207
	v_pk_mul_f32 v[208:209], v[158:159], v[166:167]
	v_pk_mul_f32 v[210:211], v[160:161], v[168:169]
	v_pk_mul_f32 v[204:205], v[162:163], v[204:205]
	v_pk_mul_f32 v[206:207], v[164:165], v[206:207]
	ds_read_b128 v[150:153], v230 offset:256
	ds_read_b128 v[154:157], v230 offset:640
	ds_read_b128 v[158:161], v230 offset:1024
	ds_read_b128 v[162:165], v231 offset:256
	v_exp_f32_e32 v166, v208
	v_exp_f32_e32 v167, v209
	v_exp_f32_e32 v168, v210
	v_exp_f32_e32 v169, v211
	v_pk_fma_f32 v[216:217], v[208:209], s[4:5], v[248:249] op_sel:[0,1,0] op_sel_hi:[1,1,0]
	v_pk_fma_f32 v[218:219], v[210:211], s[4:5], v[248:249] op_sel:[0,1,0] op_sel_hi:[1,1,0]
	v_pk_fma_f32 v[216:217], v[208:209], v[216:217], v[248:249] op_sel:[0,0,1] op_sel_hi:[1,1,1]
	v_pk_fma_f32 v[218:219], v[210:211], v[218:219], v[248:249] op_sel:[0,0,1] op_sel_hi:[1,1,1]
	v_min3_f32 v212, v208, v209, v210
	v_pk_fma_f32 v[216:217], v[208:209], v[216:217], v[250:251] op_sel_hi:[1,1,0]
	v_pk_fma_f32 v[218:219], v[210:211], v[218:219], v[250:251] op_sel_hi:[1,1,0]
	v_min_f32_e32 v212, v212, v211
	v_pk_fma_f32 v[216:217], v[208:209], v[216:217], v[250:251] op_sel:[0,0,1] op_sel_hi:[1,1,1]
	v_pk_fma_f32 v[218:219], v[210:211], v[218:219], v[250:251] op_sel:[0,0,1] op_sel_hi:[1,1,1]
	v_cmp_nlt_f32_e32 vcc, 0xbe38aa3b, v212
	v_pk_mul_f32 v[216:217], v[216:217], v[208:209]
	v_pk_mul_f32 v[218:219], v[218:219], v[210:211]
	s_cbranch_vccnz .Lscan2_far3
.Lscan2_back3:
	v_sqrt_f32_e32 v216, v216
	v_sqrt_f32_e32 v217, v217
	v_sqrt_f32_e32 v218, v218
	v_sqrt_f32_e32 v219, v219
	v_pk_mul_f32 v[204:205], v[204:205], v[216:217]
	v_pk_mul_f32 v[206:207], v[206:207], v[218:219]
	s_waitcnt lgkmcnt(0)
	v_mfma_f32_16x16x32_bf16 v[134:137], v[110:113], v[98:101], 0
	v_mfma_f32_16x16x32_bf16 v[138:141], v[122:125], v[98:101], 0
	v_mfma_f32_16x16x32_bf16 v[134:137], v[114:117], v[102:105], v[134:137]
	v_mfma_f32_16x16x32_bf16 v[138:141], v[126:129], v[102:105], v[138:141]
	v_mfma_f32_16x16x32_bf16 v[134:137], v[118:121], v[106:109], v[134:137]
	v_mfma_f32_16x16x32_bf16 v[138:141], v[130:133], v[106:109], v[138:141]
	s_nop 1
	v_fmac_f32_dpp v204, v204, v166 row_shr:1 row_mask:0xf bank_mask:0xf bound_ctrl:1
	v_fmac_f32_dpp v205, v205, v167 row_shr:1 row_mask:0xf bank_mask:0xf bound_ctrl:1
	v_fmac_f32_dpp v206, v206, v168 row_shr:1 row_mask:0xf bank_mask:0xf bound_ctrl:1
	v_fmac_f32_dpp v207, v207, v169 row_shr:1 row_mask:0xf bank_mask:0xf bound_ctrl:1
	v_mul_f32_dpp v166, v166, v166 row_shr:1 row_mask:0xf bank_mask:0xf
	v_mul_f32_dpp v167, v167, v167 row_shr:1 row_mask:0xf bank_mask:0xf
	v_mul_f32_dpp v168, v168, v168 row_shr:1 row_mask:0xf bank_mask:0xf
	v_mul_f32_dpp v169, v169, v169 row_shr:1 row_mask:0xf bank_mask:0xf
	v_fmac_f32_dpp v204, v204, v166 row_shr:2 row_mask:0xf bank_mask:0xf bound_ctrl:1
	v_fmac_f32_dpp v205, v205, v167 row_shr:2 row_mask:0xf bank_mask:0xf bound_ctrl:1
	v_fmac_f32_dpp v206, v206, v168 row_shr:2 row_mask:0xf bank_mask:0xf bound_ctrl:1
	v_fmac_f32_dpp v207, v207, v169 row_shr:2 row_mask:0xf bank_mask:0xf bound_ctrl:1
	v_mul_f32_dpp v166, v166, v166 row_shr:2 row_mask:0xf bank_mask:0xf
	v_mul_f32_dpp v167, v167, v167 row_shr:2 row_mask:0xf bank_mask:0xf
	v_mul_f32_dpp v168, v168, v168 row_shr:2 row_mask:0xf bank_mask:0xf
	v_mul_f32_dpp v169, v169, v169 row_shr:2 row_mask:0xf bank_mask:0xf
	v_fmac_f32_dpp v204, v204, v166 row_shr:4 row_mask:0xf bank_mask:0xf bound_ctrl:1
	v_fmac_f32_dpp v205, v205, v167 row_shr:4 row_mask:0xf bank_mask:0xf bound_ctrl:1
	v_fmac_f32_dpp v206, v206, v168 row_shr:4 row_mask:0xf bank_mask:0xf bound_ctrl:1
	v_fmac_f32_dpp v207, v207, v169 row_shr:4 row_mask:0xf bank_mask:0xf bound_ctrl:1
	v_mul_f32_dpp v166, v166, v166 row_shr:4 row_mask:0xf bank_mask:0xf
	v_mul_f32_dpp v167, v167, v167 row_shr:4 row_mask:0xf bank_mask:0xf
	v_mul_f32_dpp v168, v168, v168 row_shr:4 row_mask:0xf bank_mask:0xf
	v_mul_f32_dpp v169, v169, v169 row_shr:4 row_mask:0xf bank_mask:0xf
	v_fmac_f32_dpp v204, v204, v166 row_shr:8 row_mask:0xf bank_mask:0xf bound_ctrl:1
	v_fmac_f32_dpp v205, v205, v167 row_shr:8 row_mask:0xf bank_mask:0xf bound_ctrl:1
	v_fmac_f32_dpp v206, v206, v168 row_shr:8 row_mask:0xf bank_mask:0xf bound_ctrl:1
	v_fmac_f32_dpp v207, v207, v169 row_shr:8 row_mask:0xf bank_mask:0xf bound_ctrl:1
	v_mul_f32_dpp v166, v166, v166 row_shr:8 row_mask:0xf bank_mask:0xf
	v_mul_f32_dpp v167, v167, v167 row_shr:8 row_mask:0xf bank_mask:0xf
	v_mul_f32_dpp v168, v168, v168 row_shr:8 row_mask:0xf bank_mask:0xf
	v_mul_f32_dpp v169, v169, v169 row_shr:8 row_mask:0xf bank_mask:0xf
	v_fma_f32 v208, v166, v12, v204
	v_fma_f32 v209, v167, v13, v205
	v_fma_f32 v210, v168, v14, v206
	v_fma_f32 v211, v169, v15, v207
	ds_bpermute_b32 v12, v232, v208
	ds_bpermute_b32 v13, v232, v209
	ds_bpermute_b32 v14, v232, v210
	ds_bpermute_b32 v15, v232, v211
	s_waitcnt vmcnt(21)
	v_lshlrev_b32_e32 v212, 16, v30
	v_and_b32_e32 v213, 0xffff0000, v30
	v_lshlrev_b32_e32 v214, 16, v31
	v_and_b32_e32 v215, 0xffff0000, v31
	v_pk_mul_f32 v[216:217], v[212:213], v[212:213]
	v_pk_mul_f32 v[218:219], v[214:215], v[214:215]
	v_pk_fma_f32 v[216:217], v[216:217], v[36:37], v[36:37] op_sel:[0,0,1] op_sel_hi:[1,0,1]
	v_pk_fma_f32 v[218:219], v[218:219], v[36:37], v[36:37] op_sel:[0,0,1] op_sel_hi:[1,0,1]
	v_pk_mul_f32 v[216:217], v[212:213], v[216:217]
	v_pk_mul_f32 v[218:219], v[214:215], v[218:219]
	v_exp_f32_e32 v216, v216
	v_exp_f32_e32 v217, v217
	v_exp_f32_e32 v218, v218
	v_exp_f32_e32 v219, v219
	v_pk_add_f32 v[216:217], v[216:217], 1.0 op_sel_hi:[1,0]
	v_pk_add_f32 v[218:219], v[218:219], 1.0 op_sel_hi:[1,0]
	v_rcp_f32_e32 v216, v216
	v_rcp_f32_e32 v217, v217
	v_rcp_f32_e32 v218, v218
	v_rcp_f32_e32 v219, v219
	v_pk_mul_f32 v[216:217], v[212:213], v[216:217]
	v_pk_mul_f32 v[218:219], v[214:215], v[218:219]
	v_pk_mul_f32 v[216:217], v[216:217], v[208:209]
	v_pk_mul_f32 v[218:219], v[218:219], v[210:211]
	v_cvt_pk_bf16_f32 v242, v216, v217
	v_cvt_pk_bf16_f32 v243, v218, v219
	global_store_dwordx2 v236, v[242:243], s[100:101] offset:96
	ds_read_b128 v[110:113], v229 offset:16640
	ds_read_b128 v[122:125], v229 offset:36608
	ds_read_b128 v[114:117], v229 offset:16704
	ds_read_b128 v[126:129], v229 offset:36672
	ds_read_b128 v[118:121], v229 offset:16768
	ds_read_b128 v[130:133], v229 offset:36736
	v_pk_fma_f32 v[166:167], v[134:135], s[4:5], v[150:151] op_sel_hi:[1,0,1]
	v_pk_fma_f32 v[168:169], v[136:137], s[4:5], v[152:153] op_sel_hi:[1,0,1]
	v_pk_fma_f32 v[204:205], v[138:139], s[4:5], v[154:155] op_sel_hi:[1,0,1]
	v_pk_fma_f32 v[206:207], v[140:141], s[4:5], v[156:157] op_sel_hi:[1,0,1]
	v_exp_f32_e32 v166, v166
	v_exp_f32_e32 v167, v167
	v_exp_f32_e32 v168, v168
	v_exp_f32_e32 v169, v169
	v_exp_f32_e32 v204, v204
	v_exp_f32_e32 v205, v205
	v_exp_f32_e32 v206, v206
	v_exp_f32_e32 v207, v207
	v_pk_add_f32 v[166:167], v[166:167], 1.0 op_sel_hi:[1,0]
	v_pk_add_f32 v[168:169], v[168:169], 1.0 op_sel_hi:[1,0]
	v_pk_add_f32 v[204:205], v[204:205], 1.0 op_sel_hi:[1,0]
	v_pk_add_f32 v[206:207], v[206:207], 1.0 op_sel_hi:[1,0]
	v_rcp_f32_e32 v166, v166
	v_rcp_f32_e32 v167, v167
	v_rcp_f32_e32 v168, v168
	v_rcp_f32_e32 v169, v169
	v_rcp_f32_e32 v204, v204
	v_rcp_f32_e32 v205, v205
	v_rcp_f32_e32 v206, v206
	v_rcp_f32_e32 v207, v207
	v_pk_mul_f32 v[208:209], v[158:159], v[166:167]
	v_pk_mul_f32 v[210:211], v[160:161], v[168:169]
	v_pk_mul_f32 v[204:205], v[162:163], v[204:205]
	v_pk_mul_f32 v[206:207], v[164:165], v[206:207]
	ds_read_b128 v[150:153], v230 offset:320
	ds_read_b128 v[154:157], v230 offset:704
	ds_read_b128 v[158:161], v230 offset:1088
	ds_read_b128 v[162:165], v231 offset:320
	v_exp_f32_e32 v166, v208
	v_exp_f32_e32 v167, v209
	v_exp_f32_e32 v168, v210
	v_exp_f32_e32 v169, v211
	v_pk_fma_f32 v[216:217], v[208:209], s[4:5], v[248:249] op_sel:[0,1,0] op_sel_hi:[1,1,0]
	v_pk_fma_f32 v[218:219], v[210:211], s[4:5], v[248:249] op_sel:[0,1,0] op_sel_hi:[1,1,0]
	v_pk_fma_f32 v[216:217], v[208:209], v[216:217], v[248:249] op_sel:[0,0,1] op_sel_hi:[1,1,1]
	v_pk_fma_f32 v[218:219], v[210:211], v[218:219], v[248:249] op_sel:[0,0,1] op_sel_hi:[1,1,1]
	v_min3_f32 v212, v208, v209, v210
	v_pk_fma_f32 v[216:217], v[208:209], v[216:217], v[250:251] op_sel_hi:[1,1,0]
	v_pk_fma_f32 v[218:219], v[210:211], v[218:219], v[250:251] op_sel_hi:[1,1,0]
	v_min_f32_e32 v212, v212, v211
	v_pk_fma_f32 v[216:217], v[208:209], v[216:217], v[250:251] op_sel:[0,0,1] op_sel_hi:[1,1,1]
	v_pk_fma_f32 v[218:219], v[210:211], v[218:219], v[250:251] op_sel:[0,0,1] op_sel_hi:[1,1,1]
	v_cmp_nlt_f32_e32 vcc, 0xbe38aa3b, v212
	v_pk_mul_f32 v[216:217], v[216:217], v[208:209]
	v_pk_mul_f32 v[218:219], v[218:219], v[210:211]
	s_cbranch_vccnz .Lscan2_far4
.Lscan2_back4:
	v_sqrt_f32_e32 v216, v216
	v_sqrt_f32_e32 v217, v217
	v_sqrt_f32_e32 v218, v218
	v_sqrt_f32_e32 v219, v219
	v_pk_mul_f32 v[204:205], v[204:205], v[216:217]
	v_pk_mul_f32 v[206:207], v[206:207], v[218:219]
	s_waitcnt lgkmcnt(0)
	v_mfma_f32_16x16x32_bf16 v[142:145], v[110:113], v[98:101], 0
	v_mfma_f32_16x16x32_bf16 v[146:149], v[122:125], v[98:101], 0
	v_mfma_f32_16x16x32_bf16 v[142:145], v[114:117], v[102:105], v[142:145]
	v_mfma_f32_16x16x32_bf16 v[146:149], v[126:129], v[102:105], v[146:149]
	v_mfma_f32_16x16x32_bf16 v[142:145], v[118:121], v[106:109], v[142:145]
	v_mfma_f32_16x16x32_bf16 v[146:149], v[130:133], v[106:109], v[146:149]
	s_nop 1
	v_fmac_f32_dpp v204, v204, v166 row_shr:1 row_mask:0xf bank_mask:0xf bound_ctrl:1
	v_fmac_f32_dpp v205, v205, v167 row_shr:1 row_mask:0xf bank_mask:0xf bound_ctrl:1
	v_fmac_f32_dpp v206, v206, v168 row_shr:1 row_mask:0xf bank_mask:0xf bound_ctrl:1
	v_fmac_f32_dpp v207, v207, v169 row_shr:1 row_mask:0xf bank_mask:0xf bound_ctrl:1
	v_mul_f32_dpp v166, v166, v166 row_shr:1 row_mask:0xf bank_mask:0xf
	v_mul_f32_dpp v167, v167, v167 row_shr:1 row_mask:0xf bank_mask:0xf
	v_mul_f32_dpp v168, v168, v168 row_shr:1 row_mask:0xf bank_mask:0xf
	v_mul_f32_dpp v169, v169, v169 row_shr:1 row_mask:0xf bank_mask:0xf
	v_fmac_f32_dpp v204, v204, v166 row_shr:2 row_mask:0xf bank_mask:0xf bound_ctrl:1
	v_fmac_f32_dpp v205, v205, v167 row_shr:2 row_mask:0xf bank_mask:0xf bound_ctrl:1
	v_fmac_f32_dpp v206, v206, v168 row_shr:2 row_mask:0xf bank_mask:0xf bound_ctrl:1
	v_fmac_f32_dpp v207, v207, v169 row_shr:2 row_mask:0xf bank_mask:0xf bound_ctrl:1
	v_mul_f32_dpp v166, v166, v166 row_shr:2 row_mask:0xf bank_mask:0xf
	v_mul_f32_dpp v167, v167, v167 row_shr:2 row_mask:0xf bank_mask:0xf
	v_mul_f32_dpp v168, v168, v168 row_shr:2 row_mask:0xf bank_mask:0xf
	v_mul_f32_dpp v169, v169, v169 row_shr:2 row_mask:0xf bank_mask:0xf
	v_fmac_f32_dpp v204, v204, v166 row_shr:4 row_mask:0xf bank_mask:0xf bound_ctrl:1
	v_fmac_f32_dpp v205, v205, v167 row_shr:4 row_mask:0xf bank_mask:0xf bound_ctrl:1
	v_fmac_f32_dpp v206, v206, v168 row_shr:4 row_mask:0xf bank_mask:0xf bound_ctrl:1
	v_fmac_f32_dpp v207, v207, v169 row_shr:4 row_mask:0xf bank_mask:0xf bound_ctrl:1
	v_mul_f32_dpp v166, v166, v166 row_shr:4 row_mask:0xf bank_mask:0xf
	v_mul_f32_dpp v167, v167, v167 row_shr:4 row_mask:0xf bank_mask:0xf
	v_mul_f32_dpp v168, v168, v168 row_shr:4 row_mask:0xf bank_mask:0xf
	v_mul_f32_dpp v169, v169, v169 row_shr:4 row_mask:0xf bank_mask:0xf
	v_fmac_f32_dpp v204, v204, v166 row_shr:8 row_mask:0xf bank_mask:0xf bound_ctrl:1
	v_fmac_f32_dpp v205, v205, v167 row_shr:8 row_mask:0xf bank_mask:0xf bound_ctrl:1
	v_fmac_f32_dpp v206, v206, v168 row_shr:8 row_mask:0xf bank_mask:0xf bound_ctrl:1
	v_fmac_f32_dpp v207, v207, v169 row_shr:8 row_mask:0xf bank_mask:0xf bound_ctrl:1
	v_mul_f32_dpp v166, v166, v166 row_shr:8 row_mask:0xf bank_mask:0xf
	v_mul_f32_dpp v167, v167, v167 row_shr:8 row_mask:0xf bank_mask:0xf
	v_mul_f32_dpp v168, v168, v168 row_shr:8 row_mask:0xf bank_mask:0xf
	v_mul_f32_dpp v169, v169, v169 row_shr:8 row_mask:0xf bank_mask:0xf
	v_fma_f32 v208, v166, v16, v204
	v_fma_f32 v209, v167, v17, v205
	v_fma_f32 v210, v168, v18, v206
	v_fma_f32 v211, v169, v19, v207
	ds_bpermute_b32 v16, v232, v208
	ds_bpermute_b32 v17, v232, v209
	ds_bpermute_b32 v18, v232, v210
	ds_bpermute_b32 v19, v232, v211
	s_waitcnt vmcnt(21)
	v_lshlrev_b32_e32 v212, 16, v32
	v_and_b32_e32 v213, 0xffff0000, v32
	v_lshlrev_b32_e32 v214, 16, v33
	v_and_b32_e32 v215, 0xffff0000, v33
	v_pk_mul_f32 v[216:217], v[212:213], v[212:213]
	v_pk_mul_f32 v[218:219], v[214:215], v[214:215]
	v_pk_fma_f32 v[216:217], v[216:217], v[36:37], v[36:37] op_sel:[0,0,1] op_sel_hi:[1,0,1]
	v_pk_fma_f32 v[218:219], v[218:219], v[36:37], v[36:37] op_sel:[0,0,1] op_sel_hi:[1,0,1]
	v_pk_mul_f32 v[216:217], v[212:213], v[216:217]
	v_pk_mul_f32 v[218:219], v[214:215], v[218:219]
	v_exp_f32_e32 v216, v216
	v_exp_f32_e32 v217, v217
	v_exp_f32_e32 v218, v218
	v_exp_f32_e32 v219, v219
	v_pk_add_f32 v[216:217], v[216:217], 1.0 op_sel_hi:[1,0]
	v_pk_add_f32 v[218:219], v[218:219], 1.0 op_sel_hi:[1,0]
	v_rcp_f32_e32 v216, v216
	v_rcp_f32_e32 v217, v217
	v_rcp_f32_e32 v218, v218
	v_rcp_f32_e32 v219, v219
	v_pk_mul_f32 v[216:217], v[212:213], v[216:217]
	v_pk_mul_f32 v[218:219], v[214:215], v[218:219]
	v_pk_mul_f32 v[216:217], v[216:217], v[208:209]
	v_pk_mul_f32 v[218:219], v[218:219], v[210:211]
	v_cvt_pk_bf16_f32 v242, v216, v217
	v_cvt_pk_bf16_f32 v243, v218, v219
	global_store_dwordx2 v236, v[242:243], s[100:101] offset:128
	v_pk_fma_f32 v[166:167], v[142:143], s[4:5], v[150:151] op_sel_hi:[1,0,1]
	v_pk_fma_f32 v[168:169], v[144:145], s[4:5], v[152:153] op_sel_hi:[1,0,1]
	v_pk_fma_f32 v[204:205], v[146:147], s[4:5], v[154:155] op_sel_hi:[1,0,1]
	v_pk_fma_f32 v[206:207], v[148:149], s[4:5], v[156:157] op_sel_hi:[1,0,1]
	v_exp_f32_e32 v166, v166
	v_exp_f32_e32 v167, v167
	v_exp_f32_e32 v168, v168
	v_exp_f32_e32 v169, v169
	v_exp_f32_e32 v204, v204
	v_exp_f32_e32 v205, v205
	v_exp_f32_e32 v206, v206
	v_exp_f32_e32 v207, v207
	v_pk_add_f32 v[166:167], v[166:167], 1.0 op_sel_hi:[1,0]
	v_pk_add_f32 v[168:169], v[168:169], 1.0 op_sel_hi:[1,0]
	v_pk_add_f32 v[204:205], v[204:205], 1.0 op_sel_hi:[1,0]
	v_pk_add_f32 v[206:207], v[206:207], 1.0 op_sel_hi:[1,0]
	v_rcp_f32_e32 v166, v166
	v_rcp_f32_e32 v167, v167
	v_rcp_f32_e32 v168, v168
	v_rcp_f32_e32 v169, v169
	v_rcp_f32_e32 v204, v204
	v_rcp_f32_e32 v205, v205
	v_rcp_f32_e32 v206, v206
	v_rcp_f32_e32 v207, v207
	v_pk_mul_f32 v[208:209], v[158:159], v[166:167]
	v_pk_mul_f32 v[210:211], v[160:161], v[168:169]
	v_pk_mul_f32 v[204:205], v[162:163], v[204:205]
	v_pk_mul_f32 v[206:207], v[164:165], v[206:207]
	v_exp_f32_e32 v166, v208
	v_exp_f32_e32 v167, v209
	v_exp_f32_e32 v168, v210
	v_exp_f32_e32 v169, v211
	v_pk_fma_f32 v[216:217], v[208:209], s[4:5], v[248:249] op_sel:[0,1,0] op_sel_hi:[1,1,0]
	v_pk_fma_f32 v[218:219], v[210:211], s[4:5], v[248:249] op_sel:[0,1,0] op_sel_hi:[1,1,0]
	v_pk_fma_f32 v[216:217], v[208:209], v[216:217], v[248:249] op_sel:[0,0,1] op_sel_hi:[1,1,1]
	v_pk_fma_f32 v[218:219], v[210:211], v[218:219], v[248:249] op_sel:[0,0,1] op_sel_hi:[1,1,1]
	v_min3_f32 v212, v208, v209, v210
	v_pk_fma_f32 v[216:217], v[208:209], v[216:217], v[250:251] op_sel_hi:[1,1,0]
	v_pk_fma_f32 v[218:219], v[210:211], v[218:219], v[250:251] op_sel_hi:[1,1,0]
	v_min_f32_e32 v212, v212, v211
	v_pk_fma_f32 v[216:217], v[208:209], v[216:217], v[250:251] op_sel:[0,0,1] op_sel_hi:[1,1,1]
	v_pk_fma_f32 v[218:219], v[210:211], v[218:219], v[250:251] op_sel:[0,0,1] op_sel_hi:[1,1,1]
	v_cmp_nlt_f32_e32 vcc, 0xbe38aa3b, v212
	v_pk_mul_f32 v[216:217], v[216:217], v[208:209]
	v_pk_mul_f32 v[218:219], v[218:219], v[210:211]
	s_cbranch_vccnz .Lscan2_far5
.Lscan2_back5:
	v_sqrt_f32_e32 v216, v216
	v_sqrt_f32_e32 v217, v217
	v_sqrt_f32_e32 v218, v218
	v_sqrt_f32_e32 v219, v219
	v_pk_mul_f32 v[204:205], v[204:205], v[216:217]
	v_pk_mul_f32 v[206:207], v[206:207], v[218:219]
	s_waitcnt lgkmcnt(0)
	s_nop 1
	v_fmac_f32_dpp v204, v204, v166 row_shr:1 row_mask:0xf bank_mask:0xf bound_ctrl:1
	v_fmac_f32_dpp v205, v205, v167 row_shr:1 row_mask:0xf bank_mask:0xf bound_ctrl:1
	v_fmac_f32_dpp v206, v206, v168 row_shr:1 row_mask:0xf bank_mask:0xf bound_ctrl:1
	v_fmac_f32_dpp v207, v207, v169 row_shr:1 row_mask:0xf bank_mask:0xf bound_ctrl:1
	v_mul_f32_dpp v166, v166, v166 row_shr:1 row_mask:0xf bank_mask:0xf
	v_mul_f32_dpp v167, v167, v167 row_shr:1 row_mask:0xf bank_mask:0xf
	v_mul_f32_dpp v168, v168, v168 row_shr:1 row_mask:0xf bank_mask:0xf
	v_mul_f32_dpp v169, v169, v169 row_shr:1 row_mask:0xf bank_mask:0xf
	v_fmac_f32_dpp v204, v204, v166 row_shr:2 row_mask:0xf bank_mask:0xf bound_ctrl:1
	v_fmac_f32_dpp v205, v205, v167 row_shr:2 row_mask:0xf bank_mask:0xf bound_ctrl:1
	v_fmac_f32_dpp v206, v206, v168 row_shr:2 row_mask:0xf bank_mask:0xf bound_ctrl:1
	v_fmac_f32_dpp v207, v207, v169 row_shr:2 row_mask:0xf bank_mask:0xf bound_ctrl:1
	v_mul_f32_dpp v166, v166, v166 row_shr:2 row_mask:0xf bank_mask:0xf
	v_mul_f32_dpp v167, v167, v167 row_shr:2 row_mask:0xf bank_mask:0xf
	v_mul_f32_dpp v168, v168, v168 row_shr:2 row_mask:0xf bank_mask:0xf
	v_mul_f32_dpp v169, v169, v169 row_shr:2 row_mask:0xf bank_mask:0xf
	v_fmac_f32_dpp v204, v204, v166 row_shr:4 row_mask:0xf bank_mask:0xf bound_ctrl:1
	v_fmac_f32_dpp v205, v205, v167 row_shr:4 row_mask:0xf bank_mask:0xf bound_ctrl:1
	v_fmac_f32_dpp v206, v206, v168 row_shr:4 row_mask:0xf bank_mask:0xf bound_ctrl:1
	v_fmac_f32_dpp v207, v207, v169 row_shr:4 row_mask:0xf bank_mask:0xf bound_ctrl:1
	v_mul_f32_dpp v166, v166, v166 row_shr:4 row_mask:0xf bank_mask:0xf
	v_mul_f32_dpp v167, v167, v167 row_shr:4 row_mask:0xf bank_mask:0xf
	v_mul_f32_dpp v168, v168, v168 row_shr:4 row_mask:0xf bank_mask:0xf
	v_mul_f32_dpp v169, v169, v169 row_shr:4 row_mask:0xf bank_mask:0xf
	v_fmac_f32_dpp v204, v204, v166 row_shr:8 row_mask:0xf bank_mask:0xf bound_ctrl:1
	v_fmac_f32_dpp v205, v205, v167 row_shr:8 row_mask:0xf bank_mask:0xf bound_ctrl:1
	v_fmac_f32_dpp v206, v206, v168 row_shr:8 row_mask:0xf bank_mask:0xf bound_ctrl:1
	v_fmac_f32_dpp v207, v207, v169 row_shr:8 row_mask:0xf bank_mask:0xf bound_ctrl:1
	v_mul_f32_dpp v166, v166, v166 row_shr:8 row_mask:0xf bank_mask:0xf
	v_mul_f32_dpp v167, v167, v167 row_shr:8 row_mask:0xf bank_mask:0xf
	v_mul_f32_dpp v168, v168, v168 row_shr:8 row_mask:0xf bank_mask:0xf
	v_mul_f32_dpp v169, v169, v169 row_shr:8 row_mask:0xf bank_mask:0xf
	v_fma_f32 v208, v166, v20, v204
	v_fma_f32 v209, v167, v21, v205
	v_fma_f32 v210, v168, v22, v206
	v_fma_f32 v211, v169, v23, v207
	ds_bpermute_b32 v20, v232, v208
	ds_bpermute_b32 v21, v232, v209
	ds_bpermute_b32 v22, v232, v210
	ds_bpermute_b32 v23, v232, v211
	s_waitcnt vmcnt(21)
	v_lshlrev_b32_e32 v212, 16, v34
	v_and_b32_e32 v213, 0xffff0000, v34
	v_lshlrev_b32_e32 v214, 16, v35
	v_and_b32_e32 v215, 0xffff0000, v35
	v_pk_mul_f32 v[216:217], v[212:213], v[212:213]
	v_pk_mul_f32 v[218:219], v[214:215], v[214:215]
	v_pk_fma_f32 v[216:217], v[216:217], v[36:37], v[36:37] op_sel:[0,0,1] op_sel_hi:[1,0,1]
	v_pk_fma_f32 v[218:219], v[218:219], v[36:37], v[36:37] op_sel:[0,0,1] op_sel_hi:[1,0,1]
	v_pk_mul_f32 v[216:217], v[212:213], v[216:217]
	v_pk_mul_f32 v[218:219], v[214:215], v[218:219]
	v_exp_f32_e32 v216, v216
	v_exp_f32_e32 v217, v217
	v_exp_f32_e32 v218, v218
	v_exp_f32_e32 v219, v219
	v_pk_add_f32 v[216:217], v[216:217], 1.0 op_sel_hi:[1,0]
	v_pk_add_f32 v[218:219], v[218:219], 1.0 op_sel_hi:[1,0]
	v_rcp_f32_e32 v216, v216
	v_rcp_f32_e32 v217, v217
	v_rcp_f32_e32 v218, v218
	v_rcp_f32_e32 v219, v219
	v_pk_mul_f32 v[216:217], v[212:213], v[216:217]
	v_pk_mul_f32 v[218:219], v[214:215], v[218:219]
	v_pk_mul_f32 v[216:217], v[216:217], v[208:209]
	v_pk_mul_f32 v[218:219], v[218:219], v[210:211]
	v_cvt_pk_bf16_f32 v242, v216, v217
	v_cvt_pk_bf16_f32 v243, v218, v219
	global_store_dwordx2 v236, v[242:243], s[100:101] offset:160
	s_waitcnt lgkmcnt(0)
	s_waitcnt vmcnt(6)
	v_mov_b32_e32 v66, v82
	v_mov_b32_e32 v67, v83
	v_mov_b32_e32 v68, v84
	v_mov_b32_e32 v69, v85
	v_mov_b32_e32 v70, v86
	v_mov_b32_e32 v71, v87
	v_mov_b32_e32 v72, v88
	v_mov_b32_e32 v73, v89
	v_mov_b32_e32 v74, v90
	v_mov_b32_e32 v75, v91
	v_mov_b32_e32 v76, v92
	v_mov_b32_e32 v77, v93
	v_mov_b32_e32 v78, v94
	v_mov_b32_e32 v79, v95
	v_mov_b32_e32 v80, v96
	v_mov_b32_e32 v81, v97
	s_add_u32 s6, s6, 0x18000
	s_addc_u32 s7, s7, 0
	s_add_u32 s100, s100, 0xc000
	s_addc_u32 s101, s101, 0
	s_add_i32 s64, s64, 1
	s_cmp_lt_u32 s64, 3
	s_cbranch_scc1 .Lscan2_sub
	s_add_i32 s23, s23, s42
